# adds: EpiWin GEMM K-loop 4-phase; forget-gate log epilogue without the never-taken denormal/inf handling (bit-identical); (kept) EpiPlain 4-phase, conv row pipelining, hg_out LDS read-ahead
# speedup vs baseline: 1.0096x; 1.0096x over previous
; __device__ __forceinline__ int otid() { int t = threadIdx.x; asm volatile("" : "+v"(t)); return t; }
; #define PG8_STAGE(bufoff, gbase, voff) do { _Pragma("unroll") for (int _i = 0; _i < 2; ++_i) \
;     __builtin_amdgcn_global_load_lds((const unsigned*)((const char*)(gbase) + (voff)[_i]), (LAS unsigned*)(lds + (bufoff) + ldsw + _i * 8192), 16, 0, 0); } while (0)
; #define PG8_WAIT_V(n) asm volatile("s_waitcnt vmcnt(" #n ")" ::: "memory")
; #define PG8_BAR __builtin_amdgcn_s_barrier()
; template <class Epi, bool HOOK>
; __device__ __forceinline__ void gemm_phase(LAS unsigned char* lds, const Gemm g, const StaticOrder& S, const Epi& E, const int hook_t) {
;   const int tid = otid(), wid = __builtin_amdgcn_readfirstlane(tid >> 6), lane = tid & 63, wr = wid >> 2, wc = wid & 3, fr = lane & 15, fq = lane >> 4;
;   const int K = g.K, nt = K / BK;
;   unsigned voffA[2], voffB[2];
; #pragma unroll
;   for (int i = 0; i < 2; ++i) { int R, C; stage_rc(tid * 16 + i * 8192, R, C);
;     voffA[i] = (unsigned)(R * g.lda + C) * 2u; voffB[i] = (unsigned)(R * g.ldb + C) * 2u; }
;   const size_t kstep = (size_t)(BK * 2);
;   const size_t hstepA = (size_t)HALF * g.lda * 2, hstepB = (size_t)HALF * g.ldb * 2;
;   const size_t tstepA = 2 * hstepA, tstepB = 2 * hstepB;
;   const unsigned ldsw = (unsigned)wid * 1024u;
;   const int aoff = lds_byte(wr * 64 + fr, fq * 8), boff = lds_byte(wc * 32 + fr, fq * 8);
;     ...
;   const char* cA = (const char*)g.A + (size_t)cur.pm * tstepA; const char* cB = (const char*)g.Bt + (size_t)cur.pn * tstepB;
;   PG8_STAGE(PG8_SB(0, 0), cB, voffB); PG8_STAGE(PG8_SA(0, 0), cA, voffA); PG8_STAGE(PG8_SB(0, 1), cB + hstepB, voffB); PG8_STAGE(PG8_SA(0, 1), cA + hstepA, voffA);
;   if (wr == 1) PG8_BAR;
;   PG8_WAIT_V(4); PG8_BAR;
;   PG8_STAGE(PG8_SB(1, 0), cB + kstep, voffB); PG8_STAGE(PG8_SA(1, 0), cA + kstep, voffA); PG8_STAGE(PG8_SB(1, 1), cB + hstepB + kstep, voffB);
;   PG8_WAIT_V(6); PG8_BAR;
.LBB0_211:
	v_readlane_b32 s1, v252, 33
	s_add_i32 s30, s1, -1
	s_and_b32 s1, s3, 3
	s_add_i32 m0, s19, 0x18000
	v_lshl_add_u64 v[8:9], v[8:9], 0, s[56:57]
	s_lshl_b32 s3, s4, 13
	s_lshl_b32 s5, s1, 12
	s_waitcnt vmcnt(2)
	s_barrier
	global_load_lds_dwordx4 v[8:9], off
	v_lshl_add_u64 v[6:7], v[6:7], 0, s[56:57]
	s_add_i32 m0, s19, 0x1a000
	s_add_i32 s31, s19, 0x8000
	s_add_i32 s34, s19, 0xa000
	global_load_lds_dwordx4 v[6:7], off
	v_lshl_add_u64 v[4:5], v[4:5], 0, s[56:57]
	s_mov_b32 m0, s31
	s_add_u32 s10, s20, 0x40080
	global_load_lds_dwordx4 v[4:5], off
	v_lshl_add_u64 v[2:3], v[2:3], 0, s[56:57]
	s_mov_b32 m0, s34
	s_addc_u32 s11, s21, 0
	global_load_lds_dwordx4 v[2:3], off
	s_add_i32 m0, s19, 0x1c000
	v_lshl_add_u64 v[2:3], s[10:11], 0, v[138:139]
	global_load_lds_dwordx4 v[2:3], off
	v_lshl_add_u64 v[2:3], s[10:11], 0, v[140:141]
	s_add_i32 m0, s19, 0x1e000
	s_lshr_b32 s35, s8, 3
	global_load_lds_dwordx4 v[2:3], off
	v_lshrrev_b32_e32 v2, 1, v0
	v_and_b32_e32 v2, 24, v2
	v_and_b32_e32 v3, 15, v0
	v_lshlrev_b32_e32 v4, 1, v2
	v_lshlrev_b32_e32 v0, 2, v0
	v_lshl_or_b32 v190, s4, 6, v3
	v_lshl_or_b32 v3, v3, 6, v4
	v_and_b32_e32 v0, 32, v0
	v_bitop3_b32 v191, v3, s5, v0 bitop3:0xde
	v_readlane_b32 s4, v253, 55
	v_bitop3_b32 v4, v3, s3, v0 bitop3:0xde
	v_lshlrev_b32_e32 v0, 2, v2
	v_readlane_b32 s5, v253, 56
	v_and_b32_e32 v3, 1, v10
	s_waitcnt vmcnt(6)
	v_lshl_or_b32 v192, s1, 5, v2
	v_lshl_add_u64 v[142:143], s[4:5], 0, v[0:1]
	v_readlane_b32 s4, v253, 57
	v_readlane_b32 s5, v253, 58
	s_lshl_b32 s1, s1, 6
	v_readlane_b32 s3, v253, 59
	v_lshl_add_u64 v[144:145], s[4:5], 0, v[0:1]
	v_lshlrev_b32_e32 v0, 14, v10
	v_and_b32_e32 v0, 0xffff8000, v0
	v_lshl_add_u32 v0, v11, 11, v0
	v_lshl_or_b32 v0, v3, 6, v0
	s_lshl_b32 s4, s78, 10
	v_lshl_add_u32 v146, v12, 1, v0
	v_lshlrev_b32_e32 v0, 14, v13
	s_ashr_i32 s5, s4, 31
	v_and_b32_e32 v0, 0xffff8000, v0
	s_lshl_b64 s[4:5], s[4:5], 2
	v_lshl_add_u32 v0, v14, 11, v0
	v_and_b32_e32 v3, 1, v13
	s_add_u32 s36, s3, s4
	v_readlane_b32 s3, v253, 60
	v_lshl_or_b32 v0, v3, 6, v0
	v_readlane_b32 s52, v252, 25
	s_mov_b32 s9, s51
	s_addc_u32 s37, s3, s5
	v_mov_b32_e32 v147, v1
	v_lshl_add_u32 v148, v15, 1, v0
	v_mov_b32_e32 v149, v1
	s_mov_b32 s38, 0
	v_add_u32_e32 v193, 0, v4
	s_lshl_b32 s39, s1, 1
	v_lshlrev_b32_e32 v150, 1, v2
	v_readlane_b32 s53, v252, 26
	s_barrier
	s_branch .LBB0_213

; #define PG8_STAGE(bufoff, gbase, voff) do { _Pragma("unroll") for (int _i = 0; _i < 2; ++_i) \
;     __builtin_amdgcn_global_load_lds((const unsigned*)((const char*)(gbase) + (voff)[_i]), (LAS unsigned*)(lds + (bufoff) + ldsw + _i * 8192), 16, 0, 0); } while (0)
; #define PG8_LDA(dst, b, h) do { _Pragma("unroll") for (int m = 0; m < 4; ++m) _Pragma("unroll") for (int k = 0; k < 2; ++k) dst[m][k] = *(const LAS bf16x8*)(lds + PG8_SA(b, h) + aoff + m * 2048 + k * 1024); } while (0)
; #define PG8_LDB(dst, b, h) do { _Pragma("unroll") for (int n = 0; n < 2; ++n) _Pragma("unroll") for (int k = 0; k < 2; ++k) dst[n][k] = *(const LAS bf16x8*)(lds + PG8_SB(b, h) + boff + n * 2048 + k * 1024); } while (0)
; #define PG8_MMA(ai, bj, At, Bt) do { __builtin_amdgcn_s_setprio(1); _Pragma("unroll") for (int m = 0; m < 4; ++m) _Pragma("unroll") for (int n = 0; n < 2; ++n) _Pragma("unroll") for (int k = 0; k < 2; ++k) \
;     acc[ai][bj][m][n] = __builtin_amdgcn_mfma_f32_16x16x32_bf16(Bt[n][k], At[m][k], acc[ai][bj][m][n], 0, 0, 0); __builtin_amdgcn_s_setprio(0); } while (0)
; #define PG8_WAIT_L(n) asm volatile("s_waitcnt lgkmcnt(" #n ")" ::: "memory")
; #define PG8_BAR __builtin_amdgcn_s_barrier()
; #define PG8_SCHED __builtin_amdgcn_sched_barrier(0)
; template <class Epi, bool HOOK>
; __device__ __forceinline__ void gemm_phase(LAS unsigned char* lds, const Gemm g, const StaticOrder& S, const Epi& E, const int hook_t) {
;     ...
;       const bool last = (t == nt - 2);
;       const char* a1 = cA + (size_t)(t + 1) * kstep;
;       const char* a2 = last ? nA : cA + (size_t)(t + 2) * kstep; const char* b2 = last ? nB : cB + (size_t)(t + 2) * kstep;
;       const char* a3 = a2 + kstep; const char* b3 = b2 + kstep;
;       if (HOOK) { if (t == hook_t) E.hook(acc, cur.pm, cur.pn, wr, wc, fr, fq); }
;       PG8_LDB(B0, 0, 0); PG8_SCHED; PG8_LDA(At, 0, 0); PG8_STAGE(PG8_SA(1, 1), a1 + hstepA, voffA);
;       PG8_WAIT_L(8); PG8_BAR; PG8_WAIT_L(0); PG8_MMA(0, 0, At, B0); PG8_BAR; PG8_SCHED;
;       PG8_LDB(B1, 0, 1); PG8_STAGE(PG8_SB(0, 0), b2, voffB);
;       PG8_BAR; PG8_WAIT_L(0); PG8_MMA(0, 1, At, B1); PG8_BAR;
.LBB0_216:
	s_add_u32 s20, s6, 0xfffc0080
	s_addc_u32 s21, s7, -1
	s_add_i32 s43, 0, 0x10000
	v_add_u32_e32 v0, s43, v191
	ds_read_b128 v[130:133], v0
	ds_read_b128 v[134:137], v0 offset:1024
	ds_read_b128 v[152:155], v0 offset:2048
	ds_read_b128 v[156:159], v0 offset:3072
	s_cmp_eq_u32 s42, 12
	s_cselect_b32 s23, s1, s21
	s_cselect_b32 s22, s3, s20
	s_cselect_b32 s21, s11, s41
	s_cselect_b32 s20, s13, s40
	v_lshl_add_u64 v[168:169], s[6:7], 0, v[146:147]
	s_add_i32 m0, s19, 0xc000
	ds_read_b128 v[160:163], v193
	ds_read_b128 v[164:167], v193 offset:1024
	ds_read_b128 v[194:197], v193 offset:2048
	ds_read_b128 v[198:201], v193 offset:3072
	ds_read_b128 v[202:205], v193 offset:4096
	ds_read_b128 v[206:209], v193 offset:5120
	ds_read_b128 v[210:213], v193 offset:6144
	ds_read_b128 v[214:217], v193 offset:7168
	global_load_lds_dwordx4 v[168:169], off
	v_lshl_add_u64 v[168:169], s[6:7], 0, v[148:149]
	s_add_i32 m0, s19, 0xe000
	s_nop 0
	global_load_lds_dwordx4 v[168:169], off
	s_add_i32 s46, 0, 0x14000
	v_add_u32_e32 v0, s46, v191
	s_add_i32 s43, s43, s26
	ds_read_b128 v[218:221], v0
	ds_read_b128 v[222:225], v0 offset:1024
	ds_read_b128 v[226:229], v0 offset:2048
	ds_read_b128 v[230:233], v0 offset:3072
	s_cmp_eq_u32 s42, -2
	s_cselect_b32 vcc_lo, s38, 0
	s_cmp_gt_u32 vcc_lo, 1
	s_cbranch_scc1 .Lwin_a0_relaxed
	s_waitcnt vmcnt(8) lgkmcnt(0)
	s_branch .Lwin_a0_go

; #define PG8_STAGE(bufoff, gbase, voff) do { _Pragma("unroll") for (int _i = 0; _i < 2; ++_i) \
;     __builtin_amdgcn_global_load_lds((const unsigned*)((const char*)(gbase) + (voff)[_i]), (LAS unsigned*)(lds + (bufoff) + ldsw + _i * 8192), 16, 0, 0); } while (0)
; #define PG8_LDA(dst, b, h) do { _Pragma("unroll") for (int m = 0; m < 4; ++m) _Pragma("unroll") for (int k = 0; k < 2; ++k) dst[m][k] = *(const LAS bf16x8*)(lds + PG8_SA(b, h) + aoff + m * 2048 + k * 1024); } while (0)
; #define PG8_LDB(dst, b, h) do { _Pragma("unroll") for (int n = 0; n < 2; ++n) _Pragma("unroll") for (int k = 0; k < 2; ++k) dst[n][k] = *(const LAS bf16x8*)(lds + PG8_SB(b, h) + boff + n * 2048 + k * 1024); } while (0)
; #define PG8_MMA(ai, bj, At, Bt) do { __builtin_amdgcn_s_setprio(1); _Pragma("unroll") for (int m = 0; m < 4; ++m) _Pragma("unroll") for (int n = 0; n < 2; ++n) _Pragma("unroll") for (int k = 0; k < 2; ++k) \
;     acc[ai][bj][m][n] = __builtin_amdgcn_mfma_f32_16x16x32_bf16(Bt[n][k], At[m][k], acc[ai][bj][m][n], 0, 0, 0); __builtin_amdgcn_s_setprio(0); } while (0)
; #define PG8_WAIT_V(n) asm volatile("s_waitcnt vmcnt(" #n ")" ::: "memory")
; #define PG8_WAIT_L(n) asm volatile("s_waitcnt lgkmcnt(" #n ")" ::: "memory")
; #define PG8_BAR __builtin_amdgcn_s_barrier()
; #define PG8_SCHED __builtin_amdgcn_sched_barrier(0)
; template <class Epi, bool HOOK>
; __device__ __forceinline__ void gemm_phase(LAS unsigned char* lds, const Gemm g, const StaticOrder& S, const Epi& E, const int hook_t) {
;     ...
;       PG8_WAIT_L(8); PG8_BAR; PG8_WAIT_L(0); PG8_MMA(0, 0, At, B0); PG8_BAR; PG8_SCHED;
;       PG8_LDB(B1, 0, 1); PG8_STAGE(PG8_SB(0, 0), b2, voffB);
;       PG8_BAR; PG8_WAIT_L(0); PG8_MMA(0, 1, At, B1); PG8_BAR;
;       PG8_LDA(At, 0, 1); PG8_STAGE(PG8_SA(0, 0), a2, voffA);
;       PG8_BAR; PG8_WAIT_L(0); PG8_MMA(1, 0, At, B0); PG8_BAR; PG8_SCHED;
;       PG8_STAGE(PG8_SB(0, 1), b2 + hstepB, voffB);
;       PG8_WAIT_V(6); PG8_BAR; PG8_MMA(1, 1, At, B1); PG8_BAR;
.Lwin_a0_go:
	s_barrier
	s_setprio 1
	v_mfma_f32_16x16x32_bf16 v[126:129], v[130:133], v[160:163], v[126:129]
	v_mfma_f32_16x16x32_bf16 v[122:125], v[152:155], v[160:163], v[122:125]
	v_mfma_f32_16x16x32_bf16 v[110:113], v[130:133], v[194:197], v[110:113]
	v_mfma_f32_16x16x32_bf16 v[106:109], v[152:155], v[194:197], v[106:109]
	v_mfma_f32_16x16x32_bf16 v[94:97], v[130:133], v[202:205], v[94:97]
	v_mfma_f32_16x16x32_bf16 v[90:93], v[152:155], v[202:205], v[90:93]
	v_mfma_f32_16x16x32_bf16 v[78:81], v[130:133], v[210:213], v[78:81]
	v_mfma_f32_16x16x32_bf16 v[74:77], v[152:155], v[210:213], v[74:77]
	v_mfma_f32_16x16x32_bf16 v[126:129], v[134:137], v[164:167], v[126:129]
	v_mfma_f32_16x16x32_bf16 v[122:125], v[156:159], v[164:167], v[122:125]
	v_mfma_f32_16x16x32_bf16 v[110:113], v[134:137], v[198:201], v[110:113]
	v_mfma_f32_16x16x32_bf16 v[106:109], v[156:159], v[198:201], v[106:109]
	v_mfma_f32_16x16x32_bf16 v[94:97], v[134:137], v[206:209], v[94:97]
	v_mfma_f32_16x16x32_bf16 v[90:93], v[156:159], v[206:209], v[90:93]
	v_mfma_f32_16x16x32_bf16 v[78:81], v[134:137], v[214:217], v[78:81]
	v_mfma_f32_16x16x32_bf16 v[74:77], v[156:159], v[214:217], v[74:77]
	v_mfma_f32_16x16x32_bf16 v[118:121], v[218:221], v[160:163], v[118:121]
	v_mfma_f32_16x16x32_bf16 v[114:117], v[226:229], v[160:163], v[114:117]
	v_mfma_f32_16x16x32_bf16 v[102:105], v[218:221], v[194:197], v[102:105]
	v_mfma_f32_16x16x32_bf16 v[98:101], v[226:229], v[194:197], v[98:101]
	v_mfma_f32_16x16x32_bf16 v[86:89], v[218:221], v[202:205], v[86:89]
	v_mfma_f32_16x16x32_bf16 v[82:85], v[226:229], v[202:205], v[82:85]
	v_mfma_f32_16x16x32_bf16 v[70:73], v[218:221], v[210:213], v[70:73]
	v_mfma_f32_16x16x32_bf16 v[66:69], v[226:229], v[210:213], v[66:69]
	v_mfma_f32_16x16x32_bf16 v[118:121], v[222:225], v[164:167], v[118:121]
	v_mfma_f32_16x16x32_bf16 v[114:117], v[230:233], v[164:167], v[114:117]
	v_mfma_f32_16x16x32_bf16 v[102:105], v[222:225], v[198:201], v[102:105]
	v_mfma_f32_16x16x32_bf16 v[98:101], v[230:233], v[198:201], v[98:101]
	v_mfma_f32_16x16x32_bf16 v[86:89], v[222:225], v[206:209], v[86:89]
	v_mfma_f32_16x16x32_bf16 v[82:85], v[230:233], v[206:209], v[82:85]
	v_mfma_f32_16x16x32_bf16 v[70:73], v[222:225], v[214:217], v[70:73]
	v_mfma_f32_16x16x32_bf16 v[66:69], v[230:233], v[214:217], v[66:69]
	s_setprio 0
	s_barrier
	ds_read_b128 v[160:163], v193 offset:16384
	ds_read_b128 v[164:167], v193 offset:17408
	ds_read_b128 v[194:197], v193 offset:18432
	ds_read_b128 v[198:201], v193 offset:19456
	ds_read_b128 v[202:205], v193 offset:20480
	ds_read_b128 v[206:209], v193 offset:21504
	ds_read_b128 v[210:213], v193 offset:22528
	ds_read_b128 v[214:217], v193 offset:23552
	v_lshl_add_u64 v[168:169], s[20:21], 0, v[138:139]
	s_mov_b32 m0, s43
	v_lshl_add_u64 v[234:235], s[20:21], 0, v[140:141]
	global_load_lds_dwordx4 v[168:169], off
	s_add_i32 m0, s43, 0x2000
	s_nop 0
	global_load_lds_dwordx4 v[234:235], off
	s_mov_b32 m0, s19
	v_lshl_add_u64 v[236:237], s[22:23], 0, v[138:139]
	global_load_lds_dwordx4 v[236:237], off
	v_lshl_add_u64 v[238:239], s[22:23], 0, v[140:141]
	s_mov_b32 m0, s27
	s_nop 0
	global_load_lds_dwordx4 v[238:239], off
	s_add_u32 s44, s20, 0x40000
	s_addc_u32 s45, s21, 0
	s_add_i32 s43, s46, s26
	v_lshl_add_u64 v[240:241], s[44:45], 0, v[138:139]
	s_mov_b32 m0, s43
	s_nop 0
	global_load_lds_dwordx4 v[240:241], off
	v_lshl_add_u64 v[240:241], s[44:45], 0, v[140:141]
	s_add_i32 m0, s43, 0x2000
	s_nop 0
	global_load_lds_dwordx4 v[240:241], off
	s_cmp_eq_u32 s42, -2
	s_cselect_b32 vcc_lo, s38, 0
	s_cmp_gt_u32 vcc_lo, 1
	s_cbranch_scc1 .Lwin_b0_relaxed
	s_waitcnt vmcnt(8) lgkmcnt(0)
	s_branch .Lwin_b0_go

; #define PG8_STAGE(bufoff, gbase, voff) do { _Pragma("unroll") for (int _i = 0; _i < 2; ++_i) \
;     __builtin_amdgcn_global_load_lds((const unsigned*)((const char*)(gbase) + (voff)[_i]), (LAS unsigned*)(lds + (bufoff) + ldsw + _i * 8192), 16, 0, 0); } while (0)
; #define PG8_LDA(dst, b, h) do { _Pragma("unroll") for (int m = 0; m < 4; ++m) _Pragma("unroll") for (int k = 0; k < 2; ++k) dst[m][k] = *(const LAS bf16x8*)(lds + PG8_SA(b, h) + aoff + m * 2048 + k * 1024); } while (0)
; #define PG8_LDB(dst, b, h) do { _Pragma("unroll") for (int n = 0; n < 2; ++n) _Pragma("unroll") for (int k = 0; k < 2; ++k) dst[n][k] = *(const LAS bf16x8*)(lds + PG8_SB(b, h) + boff + n * 2048 + k * 1024); } while (0)
; #define PG8_MMA(ai, bj, At, Bt) do { __builtin_amdgcn_s_setprio(1); _Pragma("unroll") for (int m = 0; m < 4; ++m) _Pragma("unroll") for (int n = 0; n < 2; ++n) _Pragma("unroll") for (int k = 0; k < 2; ++k) \
;     acc[ai][bj][m][n] = __builtin_amdgcn_mfma_f32_16x16x32_bf16(Bt[n][k], At[m][k], acc[ai][bj][m][n], 0, 0, 0); __builtin_amdgcn_s_setprio(0); } while (0)
; #define PG8_WAIT_V(n) asm volatile("s_waitcnt vmcnt(" #n ")" ::: "memory")
; #define PG8_WAIT_L(n) asm volatile("s_waitcnt lgkmcnt(" #n ")" ::: "memory")
; #define PG8_BAR __builtin_amdgcn_s_barrier()
; #define PG8_SCHED __builtin_amdgcn_sched_barrier(0)
; template <class Epi, bool HOOK>
; __device__ __forceinline__ void gemm_phase(LAS unsigned char* lds, const Gemm g, const StaticOrder& S, const Epi& E, const int hook_t) {
;     ...
;       PG8_WAIT_V(6); PG8_BAR; PG8_MMA(1, 1, At, B1); PG8_BAR;
;       PG8_LDB(B0, 1, 0); PG8_SCHED; PG8_LDA(At, 1, 0); PG8_STAGE(PG8_SA(0, 1), a2 + hstepA, voffA);
;       PG8_WAIT_L(8); PG8_BAR; PG8_WAIT_L(0); PG8_MMA(0, 0, At, B0); PG8_BAR; PG8_SCHED;
;       PG8_LDB(B1, 1, 1); PG8_STAGE(PG8_SB(1, 0), b3, voffB);
;       PG8_BAR; PG8_WAIT_L(0); PG8_MMA(0, 1, At, B1); PG8_BAR;
.Lwin_b0_go:
	s_barrier
	s_setprio 1
	v_mfma_f32_16x16x32_bf16 v[62:65], v[130:133], v[160:163], v[62:65]
	v_mfma_f32_16x16x32_bf16 v[58:61], v[152:155], v[160:163], v[58:61]
	v_mfma_f32_16x16x32_bf16 v[46:49], v[130:133], v[194:197], v[46:49]
	v_mfma_f32_16x16x32_bf16 v[42:45], v[152:155], v[194:197], v[42:45]
	v_mfma_f32_16x16x32_bf16 v[30:33], v[130:133], v[202:205], v[30:33]
	v_mfma_f32_16x16x32_bf16 v[26:29], v[152:155], v[202:205], v[26:29]
	v_mfma_f32_16x16x32_bf16 v[14:17], v[130:133], v[210:213], v[14:17]
	v_mfma_f32_16x16x32_bf16 v[10:13], v[152:155], v[210:213], v[10:13]
	v_mfma_f32_16x16x32_bf16 v[62:65], v[134:137], v[164:167], v[62:65]
	v_mfma_f32_16x16x32_bf16 v[58:61], v[156:159], v[164:167], v[58:61]
	v_mfma_f32_16x16x32_bf16 v[46:49], v[134:137], v[198:201], v[46:49]
	v_mfma_f32_16x16x32_bf16 v[42:45], v[156:159], v[198:201], v[42:45]
	v_mfma_f32_16x16x32_bf16 v[30:33], v[134:137], v[206:209], v[30:33]
	v_mfma_f32_16x16x32_bf16 v[26:29], v[156:159], v[206:209], v[26:29]
	v_mfma_f32_16x16x32_bf16 v[14:17], v[134:137], v[214:217], v[14:17]
	v_mfma_f32_16x16x32_bf16 v[10:13], v[156:159], v[214:217], v[10:13]
	v_mfma_f32_16x16x32_bf16 v[54:57], v[218:221], v[160:163], v[54:57]
	v_mfma_f32_16x16x32_bf16 v[50:53], v[226:229], v[160:163], v[50:53]
	v_mfma_f32_16x16x32_bf16 v[38:41], v[218:221], v[194:197], v[38:41]
	v_mfma_f32_16x16x32_bf16 v[34:37], v[226:229], v[194:197], v[34:37]
	v_mfma_f32_16x16x32_bf16 v[22:25], v[218:221], v[202:205], v[22:25]
	v_mfma_f32_16x16x32_bf16 v[18:21], v[226:229], v[202:205], v[18:21]
	v_mfma_f32_16x16x32_bf16 v[6:9], v[218:221], v[210:213], v[6:9]
	v_mfma_f32_16x16x32_bf16 v[2:5], v[226:229], v[210:213], v[2:5]
	v_mfma_f32_16x16x32_bf16 v[54:57], v[222:225], v[164:167], v[54:57]
	v_mfma_f32_16x16x32_bf16 v[50:53], v[230:233], v[164:167], v[50:53]
	v_mfma_f32_16x16x32_bf16 v[38:41], v[222:225], v[198:201], v[38:41]
	v_mfma_f32_16x16x32_bf16 v[34:37], v[230:233], v[198:201], v[34:37]
	v_mfma_f32_16x16x32_bf16 v[22:25], v[222:225], v[206:209], v[22:25]
	v_mfma_f32_16x16x32_bf16 v[18:21], v[230:233], v[206:209], v[18:21]
	v_mfma_f32_16x16x32_bf16 v[6:9], v[222:225], v[214:217], v[6:9]
	v_mfma_f32_16x16x32_bf16 v[2:5], v[230:233], v[214:217], v[2:5]
	s_setprio 0
	s_add_i32 s43, 0, 0x18000
	v_add_u32_e32 v0, s43, v191
	s_barrier
	ds_read_b128 v[130:133], v0
	ds_read_b128 v[134:137], v0 offset:1024
	ds_read_b128 v[152:155], v0 offset:2048
	ds_read_b128 v[156:159], v0 offset:3072
	s_add_u32 s22, s22, 0x40000
	s_addc_u32 s23, s23, 0
	s_mov_b32 m0, s28
	v_lshl_add_u64 v[218:219], s[22:23], 0, v[138:139]
	ds_read_b128 v[160:163], v193 offset:32768
	ds_read_b128 v[164:167], v193 offset:33792
	ds_read_b128 v[194:197], v193 offset:34816
	ds_read_b128 v[198:201], v193 offset:35840
	ds_read_b128 v[202:205], v193 offset:36864
	ds_read_b128 v[206:209], v193 offset:37888
	ds_read_b128 v[210:213], v193 offset:38912
	ds_read_b128 v[214:217], v193 offset:39936
	global_load_lds_dwordx4 v[218:219], off
	v_lshl_add_u64 v[218:219], s[22:23], 0, v[140:141]
	s_mov_b32 m0, s29
	s_nop 0
	global_load_lds_dwordx4 v[218:219], off
	s_add_i32 s22, 0, 0x1c000
	s_add_i32 s23, s43, s26
	v_add_u32_e32 v0, s22, v191
	ds_read_b128 v[218:221], v0
	ds_read_b128 v[222:225], v0 offset:1024
	ds_read_b128 v[226:229], v0 offset:2048
	ds_read_b128 v[230:233], v0 offset:3072
	s_waitcnt vmcnt(8) lgkmcnt(0)
	s_barrier
	s_setprio 1
	v_mfma_f32_16x16x32_bf16 v[126:129], v[130:133], v[160:163], v[126:129]
	v_mfma_f32_16x16x32_bf16 v[122:125], v[152:155], v[160:163], v[122:125]
	v_mfma_f32_16x16x32_bf16 v[110:113], v[130:133], v[194:197], v[110:113]
	v_mfma_f32_16x16x32_bf16 v[106:109], v[152:155], v[194:197], v[106:109]
	v_mfma_f32_16x16x32_bf16 v[94:97], v[130:133], v[202:205], v[94:97]
	v_mfma_f32_16x16x32_bf16 v[90:93], v[152:155], v[202:205], v[90:93]
	v_mfma_f32_16x16x32_bf16 v[78:81], v[130:133], v[210:213], v[78:81]
	v_mfma_f32_16x16x32_bf16 v[74:77], v[152:155], v[210:213], v[74:77]
	v_mfma_f32_16x16x32_bf16 v[126:129], v[134:137], v[164:167], v[126:129]
	v_mfma_f32_16x16x32_bf16 v[122:125], v[156:159], v[164:167], v[122:125]
	v_mfma_f32_16x16x32_bf16 v[110:113], v[134:137], v[198:201], v[110:113]
	v_mfma_f32_16x16x32_bf16 v[106:109], v[156:159], v[198:201], v[106:109]
	v_mfma_f32_16x16x32_bf16 v[94:97], v[134:137], v[206:209], v[94:97]
	v_mfma_f32_16x16x32_bf16 v[90:93], v[156:159], v[206:209], v[90:93]
	v_mfma_f32_16x16x32_bf16 v[78:81], v[134:137], v[214:217], v[78:81]
	v_mfma_f32_16x16x32_bf16 v[74:77], v[156:159], v[214:217], v[74:77]
	v_mfma_f32_16x16x32_bf16 v[118:121], v[218:221], v[160:163], v[118:121]
	v_mfma_f32_16x16x32_bf16 v[114:117], v[226:229], v[160:163], v[114:117]
	v_mfma_f32_16x16x32_bf16 v[102:105], v[218:221], v[194:197], v[102:105]
	v_mfma_f32_16x16x32_bf16 v[98:101], v[226:229], v[194:197], v[98:101]
	v_mfma_f32_16x16x32_bf16 v[86:89], v[218:221], v[202:205], v[86:89]
	v_mfma_f32_16x16x32_bf16 v[82:85], v[226:229], v[202:205], v[82:85]
	v_mfma_f32_16x16x32_bf16 v[70:73], v[218:221], v[210:213], v[70:73]
	v_mfma_f32_16x16x32_bf16 v[66:69], v[226:229], v[210:213], v[66:69]
	v_mfma_f32_16x16x32_bf16 v[118:121], v[222:225], v[164:167], v[118:121]
	v_mfma_f32_16x16x32_bf16 v[114:117], v[230:233], v[164:167], v[114:117]
	v_mfma_f32_16x16x32_bf16 v[102:105], v[222:225], v[198:201], v[102:105]
	v_mfma_f32_16x16x32_bf16 v[98:101], v[230:233], v[198:201], v[98:101]
	v_mfma_f32_16x16x32_bf16 v[86:89], v[222:225], v[206:209], v[86:89]
	v_mfma_f32_16x16x32_bf16 v[82:85], v[230:233], v[206:209], v[82:85]
	v_mfma_f32_16x16x32_bf16 v[70:73], v[222:225], v[214:217], v[70:73]
	v_mfma_f32_16x16x32_bf16 v[66:69], v[230:233], v[214:217], v[66:69]
	s_setprio 0
	s_barrier
; __device__ __forceinline__ float sigm(float x) { return __builtin_amdgcn_rcpf(1.f + fexp(-x)); }
; #define PG8_STAGE(bufoff, gbase, voff) do { _Pragma("unroll") for (int _i = 0; _i < 2; ++_i) \
;     __builtin_amdgcn_global_load_lds((const unsigned*)((const char*)(gbase) + (voff)[_i]), (LAS unsigned*)(lds + (bufoff) + ldsw + _i * 8192), 16, 0, 0); } while (0)
; #define PG8_LDA(dst, b, h) do { _Pragma("unroll") for (int m = 0; m < 4; ++m) _Pragma("unroll") for (int k = 0; k < 2; ++k) dst[m][k] = *(const LAS bf16x8*)(lds + PG8_SA(b, h) + aoff + m * 2048 + k * 1024); } while (0)
; #define PG8_MMA(ai, bj, At, Bt) do { __builtin_amdgcn_s_setprio(1); _Pragma("unroll") for (int m = 0; m < 4; ++m) _Pragma("unroll") for (int n = 0; n < 2; ++n) _Pragma("unroll") for (int k = 0; k < 2; ++k) \
;     acc[ai][bj][m][n] = __builtin_amdgcn_mfma_f32_16x16x32_bf16(Bt[n][k], At[m][k], acc[ai][bj][m][n], 0, 0, 0); __builtin_amdgcn_s_setprio(0); } while (0)
; #define PG8_WAIT_V(n) asm volatile("s_waitcnt vmcnt(" #n ")" ::: "memory")
; #define PG8_WAIT_L(n) asm volatile("s_waitcnt lgkmcnt(" #n ")" ::: "memory")
; template <class Epi, bool HOOK>
; __device__ __forceinline__ void gemm_phase(LAS unsigned char* lds, const Gemm g, const StaticOrder& S, const Epi& E, const int hook_t) {
;     ...
;       PG8_LDA(At, 1, 1); PG8_STAGE(PG8_SA(1, 0), a3, voffA);
;       PG8_BAR; PG8_WAIT_L(0); PG8_MMA(1, 0, At, B0); PG8_BAR; PG8_SCHED;
;       PG8_STAGE(PG8_SB(1, 1), b3 + hstepB, voffB);
;       PG8_WAIT_V(6); PG8_BAR; PG8_MMA(1, 1, At, B1); PG8_BAR;
;     }
;   __device__ __forceinline__ void operator()(const AccT& acc, int pm, int pn, int wr, int wc, int fr, int fq) const {
;     ...
;     bf16_t* dst = (bf16_t*)(ws + (seg == 0 ? OFF_QH : seg == 3 ? OFF_VH : seg == 4 ? OFF_GG : OFF_VD));
;     const int mode = seg == 0 ? 1 : (seg == 4 ? 2 : 0);
; #pragma unroll
;     for (int ai = 0; ai < 2; ++ai)
; #pragma unroll
;       for (int m = 0; m < 4; ++m) { bf16_t* rowp = dst + (size_t)(row0 + ai * 128 + m * 16) * 512 + cin;
; #pragma unroll
;         for (int bj = 0; bj < 2; ++bj) { f32x4 v0 = acc[ai][bj][m][0], v1 = acc[ai][bj][m][1];
;           if (mode) {
; #pragma unroll
;             for (int j = 0; j < 4; ++j) { v0[j] = v0[j] * sigm(v0[j]) * (mode == 1 ? 0.08838834764831845f : 1.f); v1[j] = v1[j] * sigm(v1[j]) * (mode == 1 ? 0.08838834764831845f : 1.f); } }
	ds_read_b128 v[160:163], v193 offset:49152
	ds_read_b128 v[164:167], v193 offset:50176
	ds_read_b128 v[194:197], v193 offset:51200
	ds_read_b128 v[198:201], v193 offset:52224
	ds_read_b128 v[202:205], v193 offset:53248
	ds_read_b128 v[206:209], v193 offset:54272
	ds_read_b128 v[210:213], v193 offset:55296
	ds_read_b128 v[214:217], v193 offset:56320
	s_mov_b32 m0, s23
	v_lshl_add_u64 v[168:169], v[168:169], 0, s[56:57]
	global_load_lds_dwordx4 v[168:169], off
	v_lshl_add_u64 v[168:169], v[234:235], 0, s[56:57]
	s_add_i32 m0, s23, 0x2000
	s_nop 0
	global_load_lds_dwordx4 v[168:169], off
	s_mov_b32 m0, s31
	v_lshl_add_u64 v[168:169], v[236:237], 0, s[56:57]
	global_load_lds_dwordx4 v[168:169], off
	v_lshl_add_u64 v[168:169], v[238:239], 0, s[56:57]
	s_mov_b32 m0, s34
	s_nop 0
	global_load_lds_dwordx4 v[168:169], off
	s_add_u32 s20, s20, 0x40080
	s_addc_u32 s21, s21, 0
	s_add_i32 s22, s22, s26
	v_lshl_add_u64 v[240:241], s[20:21], 0, v[138:139]
	s_mov_b32 m0, s22
	s_nop 0
	global_load_lds_dwordx4 v[240:241], off
	v_lshl_add_u64 v[240:241], s[20:21], 0, v[140:141]
	s_add_i32 m0, s22, 0x2000
	s_nop 0
	global_load_lds_dwordx4 v[240:241], off
	s_waitcnt vmcnt(8) lgkmcnt(0)
	s_barrier
	s_setprio 1
	v_mfma_f32_16x16x32_bf16 v[62:65], v[130:133], v[160:163], v[62:65]
	v_mfma_f32_16x16x32_bf16 v[58:61], v[152:155], v[160:163], v[58:61]
	v_mfma_f32_16x16x32_bf16 v[46:49], v[130:133], v[194:197], v[46:49]
	v_mfma_f32_16x16x32_bf16 v[42:45], v[152:155], v[194:197], v[42:45]
	v_mfma_f32_16x16x32_bf16 v[30:33], v[130:133], v[202:205], v[30:33]
	v_mfma_f32_16x16x32_bf16 v[26:29], v[152:155], v[202:205], v[26:29]
	v_mfma_f32_16x16x32_bf16 v[14:17], v[130:133], v[210:213], v[14:17]
	v_mfma_f32_16x16x32_bf16 v[10:13], v[152:155], v[210:213], v[10:13]
	v_mfma_f32_16x16x32_bf16 v[62:65], v[134:137], v[164:167], v[62:65]
	v_mfma_f32_16x16x32_bf16 v[58:61], v[156:159], v[164:167], v[58:61]
	v_mfma_f32_16x16x32_bf16 v[46:49], v[134:137], v[198:201], v[46:49]
	v_mfma_f32_16x16x32_bf16 v[42:45], v[156:159], v[198:201], v[42:45]
	v_mfma_f32_16x16x32_bf16 v[30:33], v[134:137], v[206:209], v[30:33]
	v_mfma_f32_16x16x32_bf16 v[26:29], v[156:159], v[206:209], v[26:29]
	v_mfma_f32_16x16x32_bf16 v[14:17], v[134:137], v[214:217], v[14:17]
	v_mfma_f32_16x16x32_bf16 v[10:13], v[156:159], v[214:217], v[10:13]
	v_mfma_f32_16x16x32_bf16 v[54:57], v[218:221], v[160:163], v[54:57]
	v_mfma_f32_16x16x32_bf16 v[50:53], v[226:229], v[160:163], v[50:53]
	v_mfma_f32_16x16x32_bf16 v[38:41], v[218:221], v[194:197], v[38:41]
	v_mfma_f32_16x16x32_bf16 v[34:37], v[226:229], v[194:197], v[34:37]
	v_mfma_f32_16x16x32_bf16 v[22:25], v[218:221], v[202:205], v[22:25]
	v_mfma_f32_16x16x32_bf16 v[18:21], v[226:229], v[202:205], v[18:21]
	v_mfma_f32_16x16x32_bf16 v[6:9], v[218:221], v[210:213], v[6:9]
	v_mfma_f32_16x16x32_bf16 v[2:5], v[226:229], v[210:213], v[2:5]
	v_mfma_f32_16x16x32_bf16 v[54:57], v[222:225], v[164:167], v[54:57]
	v_mfma_f32_16x16x32_bf16 v[50:53], v[230:233], v[164:167], v[50:53]
	v_mfma_f32_16x16x32_bf16 v[38:41], v[222:225], v[198:201], v[38:41]
	v_mfma_f32_16x16x32_bf16 v[34:37], v[230:233], v[198:201], v[34:37]
	v_mfma_f32_16x16x32_bf16 v[22:25], v[222:225], v[206:209], v[22:25]
	v_mfma_f32_16x16x32_bf16 v[18:21], v[230:233], v[206:209], v[18:21]
	v_mfma_f32_16x16x32_bf16 v[6:9], v[222:225], v[214:217], v[6:9]
	v_mfma_f32_16x16x32_bf16 v[2:5], v[230:233], v[214:217], v[2:5]
	s_setprio 0
	s_add_i32 s42, s42, 2
	s_add_u32 s6, s6, 0x100
	s_addc_u32 s7, s7, 0
	s_add_u32 s40, s40, 0x100
	s_addc_u32 s41, s41, 0
	s_cmp_gt_u32 s42, 13
	s_barrier
	s_cbranch_scc0 .LBB0_216
	v_lshl_add_u32 v152, s0, 8, v190
	s_cmp_lt_i32 s18, 16
	s_mov_b64 s[0:1], -1
	s_mov_b32 s40, 0x3fb8aa3b
	s_movk_i32 s41, 0x104
	s_mov_b32 s42, 0xc2ce8ed0
	s_mov_b32 s43, 0x42b17218
	s_cbranch_scc0 .LBB0_259
	s_ashr_i32 s3, s18, 1
	s_lshl_b32 s0, s18, 8
	s_and_b32 s11, s0, 0x100
	s_add_i32 s0, s3, -1
	v_or_b32_e32 v155, s11, v192
	s_cmp_gt_u32 s0, 1
	s_mov_b64 s[0:1], -1
	s_cbranch_scc0 .LBB0_256
	s_add_i32 s0, s3, -5
	s_cmp_gt_u32 s0, 1
	s_mov_b64 s[0:1], -1
	s_cbranch_scc0 .LBB0_253
	s_cmp_gt_u32 s18, 1
	s_cselect_b64 s[0:1], -1, 0
	s_cmp_lg_u32 s3, 4
	s_cselect_b64 s[6:7], -1, 0
	s_and_b64 s[6:7], s[0:1], s[6:7]
	v_mov_b64_e32 v[132:133], v[128:129]
	v_mov_b64_e32 v[136:137], v[124:125]
	v_cndmask_b32_e64 v154, v184, 1.0, s[0:1]
	s_and_b64 vcc, exec, s[6:7]
	v_mov_b64_e32 v[130:131], v[126:127]
	v_mov_b64_e32 v[134:135], v[122:123]
	s_cbranch_vccnz .LBB0_222
	v_mul_f32_e32 v0, 0xbfb8aa3b, v126
	v_exp_f32_e32 v0, v0
	v_mul_f32_e32 v130, 0xbfb8aa3b, v122
	v_exp_f32_e32 v130, v130
	v_mul_f32_e32 v132, 0xbfb8aa3b, v123
	v_add_f32_e32 v0, 1.0, v0
	v_exp_f32_e32 v132, v132
	v_add_f32_e32 v131, 1.0, v130
	v_rcp_f32_e32 v130, v0
	v_mul_f32_e32 v0, 0xbfb8aa3b, v127
	v_exp_f32_e32 v0, v0
	v_rcp_f32_e32 v134, v131
	v_add_f32_e32 v0, 1.0, v0
	v_rcp_f32_e32 v131, v0
	v_add_f32_e32 v0, 1.0, v132
	v_rcp_f32_e32 v135, v0
	v_mul_f32_e32 v0, 0xbfb8aa3b, v128
	v_mul_f32_e32 v132, 0xbfb8aa3b, v124
	v_exp_f32_e32 v0, v0
	v_exp_f32_e32 v133, v132
	v_mul_f32_e32 v132, 0xbfb8aa3b, v129
	v_exp_f32_e32 v136, v132
	v_add_f32_e32 v0, 1.0, v0
	v_rcp_f32_e32 v132, v0
	v_add_f32_e32 v0, 1.0, v133
	v_add_f32_e32 v133, 1.0, v136
	v_mul_f32_e32 v136, 0xbfb8aa3b, v125
	v_exp_f32_e32 v137, v136
	v_rcp_f32_e32 v136, v0
	v_rcp_f32_e32 v133, v133
	v_pk_mul_f32 v[130:131], v[126:127], v[130:131]
	v_add_f32_e32 v0, 1.0, v137
	v_rcp_f32_e32 v137, v0
	v_pk_mul_f32 v[132:133], v[128:129], v[132:133]
	v_pk_mul_f32 v[134:135], v[122:123], v[134:135]
	v_pk_mul_f32 v[132:133], v[154:155], v[132:133] op_sel_hi:[0,1]
	v_pk_mul_f32 v[136:137], v[124:125], v[136:137]
	v_pk_mul_f32 v[130:131], v[154:155], v[130:131] op_sel_hi:[0,1]
	v_pk_mul_f32 v[136:137], v[154:155], v[136:137] op_sel_hi:[0,1]
	v_pk_mul_f32 v[134:135], v[154:155], v[134:135] op_sel_hi:[0,1]

; __device__ __forceinline__ float sigm(float x) { return __builtin_amdgcn_rcpf(1.f + fexp(-x)); }
;   __device__ __forceinline__ void operator()(const AccT& acc, int pm, int pn, int wr, int wc, int fr, int fq) const {
;     ...
;       const int dir = seg - 1;
;       float* GF = (float*)(ws + OFF_GF);
;       const float* LB = (const float*)(ws + OFF_LB) + l * 1024 + dir * 512;
; #pragma unroll
;       for (int bj = 0; bj < 2; ++bj)
; #pragma unroll
;         for (int n = 0; n < 2; ++n) { const int c = cin + bj * 128 + n * 4; const f32x4 lb = *(const f32x4*)(LB + c);
; #pragma unroll
;           for (int ai = 0; ai < 2; ++ai)
; #pragma unroll
;             for (int m = 0; m < 4; ++m) { const f32x4 v = acc[ai][bj][m][n]; f32x4 o;
; #pragma unroll
;               for (int j = 0; j < 4; ++j) o[j] = __logf(fmaxf(lb[j], 1e-30f) + (1.f - lb[j]) * sigm(v[j]));
;               *(f32x4*)(GF + (size_t)(row0 + ai * 128 + m * 16) * 1024 + dir * 512 + c) = o; } }
.LBB0_256:
	s_andn2_b64 vcc, exec, s[0:1]
	s_cbranch_vccnz .LBB0_258
	s_lshl_b32 s0, s3, 9
	s_add_i32 s50, s0, 0xfffffe00
	s_lshl_b64 s[0:1], s[50:51], 2
	s_add_u32 s6, s36, s0
	s_addc_u32 s7, s37, s1
	v_lshlrev_b32_e32 v0, 2, v155
	global_load_dwordx4 v[130:133], v0, s[6:7] offset:16
	global_load_dwordx4 v[134:137], v0, s[6:7]
	s_add_u32 s0, s52, s0
	s_addc_u32 s1, s53, s1
	v_lshl_add_u64 v[160:161], s[0:1], 0, v[0:1]
	v_or_b32_e32 v156, 16, v152
	v_ashrrev_i32_e32 v157, 31, v156
	v_lshlrev_b64 v[156:157], 12, v[156:157]
	v_lshl_add_u64 v[156:157], v[160:161], 0, v[156:157]
	v_or_b32_e32 v158, 32, v152
	v_ashrrev_i32_e32 v159, 31, v158
	v_lshlrev_b64 v[158:159], 12, v[158:159]
	v_lshl_add_u64 v[158:159], v[160:161], 0, v[158:159]
	v_or_b32_e32 v162, 48, v152
	v_ashrrev_i32_e32 v163, 31, v162
	v_lshlrev_b64 v[162:163], 12, v[162:163]
	s_waitcnt vmcnt(0)
	v_max_f32_e32 v151, v134, v134
	v_sub_f32_e32 v198, 1.0, v134
	v_mul_f32_e32 v134, 0xbfb8aa3b, v126
	v_exp_f32_e32 v134, v134
	v_max_f32_e32 v197, 0xda24260, v151
	v_sub_f32_e32 v166, 1.0, v135
	v_sub_f32_e32 v194, 1.0, v136
	v_add_f32_e32 v134, 1.0, v134
	v_rcp_f32_e32 v134, v134
	v_sub_f32_e32 v196, 1.0, v137
	v_fma_f32 v134, v134, v198, v197
	v_log_f32_e32 v134, v134
	s_nop 0
	v_mul_f32_e32 v151, 0x3f317217, v134
	v_fma_f32 v151, v134, s62, -v151
	v_fmac_f32_e32 v151, 0x3377d1cf, v134
	v_fmac_f32_e32 v151, 0x3f317217, v134
	v_mov_b32_e32 v134, v151
	v_max_f32_e32 v151, v135, v135
	v_mul_f32_e32 v135, 0xbfb8aa3b, v127
	v_exp_f32_e32 v135, v135
	v_max_f32_e32 v151, 0xda24260, v151
	v_add_f32_e32 v135, 1.0, v135
	v_rcp_f32_e32 v135, v135
	s_nop 0
	v_fma_f32 v135, v135, v166, v151
	v_log_f32_e32 v135, v135
	s_nop 0
	v_mul_f32_e32 v153, 0x3f317217, v135
	v_fma_f32 v153, v135, s62, -v153
	v_fmac_f32_e32 v153, 0x3377d1cf, v135
	v_fmac_f32_e32 v153, 0x3f317217, v135
	v_mov_b32_e32 v135, v153
	v_max_f32_e32 v153, v136, v136
	v_mul_f32_e32 v136, 0xbfb8aa3b, v128
	v_exp_f32_e32 v136, v136
	v_max_f32_e32 v167, 0xda24260, v153
	v_add_f32_e32 v136, 1.0, v136
	v_rcp_f32_e32 v136, v136
	s_nop 0
	v_fma_f32 v136, v136, v194, v167
	v_log_f32_e32 v136, v136
	s_nop 0
	v_mul_f32_e32 v153, 0x3f317217, v136
	v_fma_f32 v153, v136, s62, -v153
	v_fmac_f32_e32 v153, 0x3377d1cf, v136
	v_fmac_f32_e32 v153, 0x3f317217, v136
	v_mov_b32_e32 v136, v153
	v_max_f32_e32 v153, v137, v137
	v_mul_f32_e32 v137, 0xbfb8aa3b, v129
	v_exp_f32_e32 v137, v137
	v_max_f32_e32 v195, 0xda24260, v153
	v_add_f32_e32 v137, 1.0, v137
	v_rcp_f32_e32 v137, v137
	s_nop 0
	v_fma_f32 v137, v137, v196, v195
	v_log_f32_e32 v137, v137
	s_nop 0
	v_mul_f32_e32 v153, 0x3f317217, v137
	v_fma_f32 v153, v137, s62, -v153
	v_fmac_f32_e32 v153, 0x3377d1cf, v137
	v_fmac_f32_e32 v153, 0x3f317217, v137
	v_mov_b32_e32 v137, v153
	v_ashrrev_i32_e32 v153, 31, v152
	v_lshlrev_b64 v[154:155], 12, v[152:153]
	v_lshl_add_u64 v[154:155], v[160:161], 0, v[154:155]
	global_store_dwordx4 v[154:155], v[134:137], off
	v_lshl_add_u64 v[160:161], v[160:161], 0, v[162:163]
	s_nop 0
	v_mul_f32_e32 v134, 0xbfb8aa3b, v110
	v_exp_f32_e32 v134, v134
	s_nop 0
	v_add_f32_e32 v134, 1.0, v134
	v_rcp_f32_e32 v134, v134
	s_nop 0
	v_fma_f32 v134, v134, v198, v197
	v_log_f32_e32 v134, v134
	s_nop 0
	v_mul_f32_e32 v135, 0x3f317217, v134
	v_fma_f32 v135, v134, s62, -v135
	v_fmac_f32_e32 v135, 0x3377d1cf, v134
	v_fmac_f32_e32 v135, 0x3f317217, v134
	v_mov_b32_e32 v134, v135
	v_mul_f32_e32 v135, 0xbfb8aa3b, v111
	v_exp_f32_e32 v135, v135
	s_nop 0
	v_add_f32_e32 v135, 1.0, v135
	v_rcp_f32_e32 v135, v135
	s_nop 0
	v_fma_f32 v135, v135, v166, v151
	v_log_f32_e32 v135, v135
	s_nop 0
	v_mul_f32_e32 v136, 0x3f317217, v135
	v_fma_f32 v136, v135, s62, -v136
	v_fmac_f32_e32 v136, 0x3377d1cf, v135
	v_fmac_f32_e32 v136, 0x3f317217, v135
	v_mov_b32_e32 v135, v136
	v_mul_f32_e32 v136, 0xbfb8aa3b, v112
	v_exp_f32_e32 v136, v136
	s_nop 0
	v_add_f32_e32 v136, 1.0, v136
	v_rcp_f32_e32 v136, v136
	s_nop 0
	v_fma_f32 v136, v136, v194, v167
	v_log_f32_e32 v136, v136
	s_nop 0
	v_mul_f32_e32 v137, 0x3f317217, v136
	v_fma_f32 v137, v136, s62, -v137
	v_fmac_f32_e32 v137, 0x3377d1cf, v136
	v_fmac_f32_e32 v137, 0x3f317217, v136
	v_mov_b32_e32 v136, v137
	v_mul_f32_e32 v137, 0xbfb8aa3b, v113
	v_exp_f32_e32 v137, v137
	s_nop 0
	v_add_f32_e32 v137, 1.0, v137
	v_rcp_f32_e32 v137, v137
	s_nop 0
	v_fma_f32 v137, v137, v196, v195
	v_log_f32_e32 v137, v137
	s_nop 0
	v_mul_f32_e32 v153, 0x3f317217, v137
	v_fma_f32 v153, v137, s62, -v153
	v_fmac_f32_e32 v153, 0x3377d1cf, v137
	v_fmac_f32_e32 v153, 0x3f317217, v137
	v_mov_b32_e32 v137, v153
	global_store_dwordx4 v[156:157], v[134:137], off
	s_nop 1
	v_mul_f32_e32 v134, 0xbfb8aa3b, v94
	v_exp_f32_e32 v134, v134
	s_nop 0
	v_add_f32_e32 v134, 1.0, v134
	v_rcp_f32_e32 v134, v134
	s_nop 0
	v_fma_f32 v134, v134, v198, v197
	v_log_f32_e32 v134, v134
	s_nop 0
	v_mul_f32_e32 v135, 0x3f317217, v134
	v_fma_f32 v135, v134, s62, -v135
	v_fmac_f32_e32 v135, 0x3377d1cf, v134
	v_fmac_f32_e32 v135, 0x3f317217, v134
	v_mov_b32_e32 v134, v135
	v_mul_f32_e32 v135, 0xbfb8aa3b, v95
	v_exp_f32_e32 v135, v135
	s_nop 0
	v_add_f32_e32 v135, 1.0, v135
	v_rcp_f32_e32 v135, v135
	s_nop 0
	v_fma_f32 v135, v135, v166, v151
	v_log_f32_e32 v135, v135
	s_nop 0
	v_mul_f32_e32 v136, 0x3f317217, v135
	v_fma_f32 v136, v135, s62, -v136
	v_fmac_f32_e32 v136, 0x3377d1cf, v135
	v_fmac_f32_e32 v136, 0x3f317217, v135
	v_mov_b32_e32 v135, v136
	v_mul_f32_e32 v136, 0xbfb8aa3b, v96
	v_exp_f32_e32 v136, v136
	s_nop 0
	v_add_f32_e32 v136, 1.0, v136
	v_rcp_f32_e32 v136, v136
	s_nop 0
	v_fma_f32 v136, v136, v194, v167
	v_log_f32_e32 v136, v136
	s_nop 0
	v_mul_f32_e32 v137, 0x3f317217, v136
	v_fma_f32 v137, v136, s62, -v137
; __device__ __forceinline__ float sigm(float x) { return __builtin_amdgcn_rcpf(1.f + fexp(-x)); }
;   __device__ __forceinline__ void operator()(const AccT& acc, int pm, int pn, int wr, int wc, int fr, int fq) const {
;     ...
;       const int dir = seg - 1;
;       float* GF = (float*)(ws + OFF_GF);
;       const float* LB = (const float*)(ws + OFF_LB) + l * 1024 + dir * 512;
; #pragma unroll
;       for (int bj = 0; bj < 2; ++bj)
; #pragma unroll
;         for (int n = 0; n < 2; ++n) { const int c = cin + bj * 128 + n * 4; const f32x4 lb = *(const f32x4*)(LB + c);
; #pragma unroll
;           for (int ai = 0; ai < 2; ++ai)
; #pragma unroll
;             for (int m = 0; m < 4; ++m) { const f32x4 v = acc[ai][bj][m][n]; f32x4 o;
; #pragma unroll
;               for (int j = 0; j < 4; ++j) o[j] = __logf(fmaxf(lb[j], 1e-30f) + (1.f - lb[j]) * sigm(v[j]));
;               *(f32x4*)(GF + (size_t)(row0 + ai * 128 + m * 16) * 1024 + dir * 512 + c) = o; } }
	v_fmac_f32_e32 v137, 0x3377d1cf, v136
	v_fmac_f32_e32 v137, 0x3f317217, v136
	v_mov_b32_e32 v136, v137
	v_mul_f32_e32 v137, 0xbfb8aa3b, v97
	v_exp_f32_e32 v137, v137
	s_nop 0
	v_add_f32_e32 v137, 1.0, v137
	v_rcp_f32_e32 v137, v137
	s_nop 0
	v_fma_f32 v137, v137, v196, v195
	v_log_f32_e32 v137, v137
	s_nop 0
	v_mul_f32_e32 v153, 0x3f317217, v137
	v_fma_f32 v153, v137, s62, -v153
	v_fmac_f32_e32 v153, 0x3377d1cf, v137
	v_fmac_f32_e32 v153, 0x3f317217, v137
	v_mov_b32_e32 v137, v153
	global_store_dwordx4 v[158:159], v[134:137], off
	s_nop 1
	v_mul_f32_e32 v134, 0xbfb8aa3b, v78
	v_exp_f32_e32 v134, v134
	s_nop 0
	v_add_f32_e32 v134, 1.0, v134
	v_rcp_f32_e32 v134, v134
	s_nop 0
	v_fma_f32 v134, v134, v198, v197
	v_log_f32_e32 v134, v134
	s_nop 0
	v_mul_f32_e32 v135, 0x3f317217, v134
	v_fma_f32 v135, v134, s62, -v135
	v_fmac_f32_e32 v135, 0x3377d1cf, v134
	v_fmac_f32_e32 v135, 0x3f317217, v134
	v_mov_b32_e32 v134, v135
	v_mul_f32_e32 v135, 0xbfb8aa3b, v79
	v_exp_f32_e32 v135, v135
	s_nop 0
	v_add_f32_e32 v135, 1.0, v135
	v_rcp_f32_e32 v135, v135
	s_nop 0
	v_fma_f32 v135, v135, v166, v151
	v_log_f32_e32 v135, v135
	s_nop 0
	v_mul_f32_e32 v136, 0x3f317217, v135
	v_fma_f32 v136, v135, s62, -v136
	v_fmac_f32_e32 v136, 0x3377d1cf, v135
	v_fmac_f32_e32 v136, 0x3f317217, v135
	v_mov_b32_e32 v135, v136
	v_mul_f32_e32 v136, 0xbfb8aa3b, v80
	v_exp_f32_e32 v136, v136
	s_nop 0
	v_add_f32_e32 v136, 1.0, v136
	v_rcp_f32_e32 v136, v136
	s_nop 0
	v_fma_f32 v136, v136, v194, v167
	v_log_f32_e32 v136, v136
	s_nop 0
	v_mul_f32_e32 v137, 0x3f317217, v136
	v_fma_f32 v137, v136, s62, -v137
	v_fmac_f32_e32 v137, 0x3377d1cf, v136
	v_fmac_f32_e32 v137, 0x3f317217, v136
	v_mov_b32_e32 v136, v137
	v_mul_f32_e32 v137, 0xbfb8aa3b, v81
	v_exp_f32_e32 v137, v137
	s_nop 0
	v_add_f32_e32 v137, 1.0, v137
	v_rcp_f32_e32 v137, v137
	s_nop 0
	v_fma_f32 v137, v137, v196, v195
	v_log_f32_e32 v137, v137
	s_nop 0
	v_mul_f32_e32 v153, 0x3f317217, v137
	v_fma_f32 v153, v137, s62, -v153
	v_fmac_f32_e32 v153, 0x3377d1cf, v137
	v_fmac_f32_e32 v153, 0x3f317217, v137
	v_mov_b32_e32 v137, v153
	global_store_dwordx4 v[160:161], v[134:137], off
	s_nop 1
	v_mul_f32_e32 v134, 0xbfb8aa3b, v62
	v_exp_f32_e32 v134, v134
	s_nop 0
	v_add_f32_e32 v134, 1.0, v134
	v_rcp_f32_e32 v134, v134
	s_nop 0
	v_fma_f32 v134, v134, v198, v197
	v_log_f32_e32 v134, v134
	s_nop 0
	v_mul_f32_e32 v135, 0x3f317217, v134
	v_fma_f32 v135, v134, s62, -v135
	v_fmac_f32_e32 v135, 0x3377d1cf, v134
	v_fmac_f32_e32 v135, 0x3f317217, v134
	v_mov_b32_e32 v134, v135
	v_mul_f32_e32 v135, 0xbfb8aa3b, v63
	v_exp_f32_e32 v135, v135
	s_nop 0
	v_add_f32_e32 v135, 1.0, v135
	v_rcp_f32_e32 v135, v135
	s_nop 0
	v_fma_f32 v135, v135, v166, v151
	v_log_f32_e32 v135, v135
	s_nop 0
	v_mul_f32_e32 v136, 0x3f317217, v135
	v_fma_f32 v136, v135, s62, -v136
	v_fmac_f32_e32 v136, 0x3377d1cf, v135
	v_fmac_f32_e32 v136, 0x3f317217, v135
	v_mov_b32_e32 v135, v136
	v_mul_f32_e32 v136, 0xbfb8aa3b, v64
	v_exp_f32_e32 v136, v136
	s_nop 0
	v_add_f32_e32 v136, 1.0, v136
	v_rcp_f32_e32 v136, v136
	s_nop 0
	v_fma_f32 v136, v136, v194, v167
	v_log_f32_e32 v136, v136
	s_nop 0
	v_mul_f32_e32 v137, 0x3f317217, v136
	v_fma_f32 v137, v136, s62, -v137
	v_fmac_f32_e32 v137, 0x3377d1cf, v136
	v_fmac_f32_e32 v137, 0x3f317217, v136
	v_mov_b32_e32 v136, v137
	v_mul_f32_e32 v137, 0xbfb8aa3b, v65
	v_exp_f32_e32 v137, v137
	s_nop 0
	v_add_f32_e32 v137, 1.0, v137
	v_rcp_f32_e32 v137, v137
	s_nop 0
	v_fma_f32 v137, v137, v196, v195
	v_cmp_gt_f32_e32 vcc, s63, v137
	s_nop 1
	v_cndmask_b32_e64 v153, 0, 32, vcc
	v_ldexp_f32 v137, v137, v153
	v_log_f32_e32 v137, v137
	s_nop 0
	v_mul_f32_e32 v153, 0x3f317217, v137
	v_fma_f32 v153, v137, s62, -v153
	v_fmac_f32_e32 v153, 0x3377d1cf, v137
	v_fmac_f32_e32 v153, 0x3f317217, v137
	v_cmp_lt_f32_e64 s[0:1], |v137|, s94
	s_nop 1
	v_cndmask_b32_e64 v137, v137, v153, s[0:1]
	s_mov_b64 s[0:1], 0x80000
	v_lshl_add_u64 v[162:163], v[154:155], 0, s[0:1]
	s_mov_b32 s0, 0x80000
	v_cndmask_b32_e32 v153, 0, v186, vcc
	v_add_co_u32_e32 v164, vcc, s0, v154
	v_sub_f32_e32 v137, v137, v153
	s_nop 0
	v_addc_co_u32_e32 v165, vcc, 0, v155, vcc
	global_store_dwordx4 v[164:165], v[134:137], off
	s_nop 1
	v_mul_f32_e32 v134, 0xbfb8aa3b, v46
	v_exp_f32_e32 v134, v134
	s_nop 0
	v_add_f32_e32 v134, 1.0, v134
	v_rcp_f32_e32 v134, v134
	s_nop 0
	v_fma_f32 v134, v134, v198, v197
	v_log_f32_e32 v134, v134
	s_nop 0
	v_mul_f32_e32 v135, 0x3f317217, v134
	v_fma_f32 v135, v134, s62, -v135
	v_fmac_f32_e32 v135, 0x3377d1cf, v134
	v_fmac_f32_e32 v135, 0x3f317217, v134
	v_mov_b32_e32 v134, v135
	v_mul_f32_e32 v135, 0xbfb8aa3b, v47
	v_exp_f32_e32 v135, v135
	s_nop 0
	v_add_f32_e32 v135, 1.0, v135
	v_rcp_f32_e32 v135, v135
	s_nop 0
	v_fma_f32 v135, v135, v166, v151
	v_log_f32_e32 v135, v135
	s_nop 0
	v_mul_f32_e32 v136, 0x3f317217, v135
	v_fma_f32 v136, v135, s62, -v136
	v_fmac_f32_e32 v136, 0x3377d1cf, v135
	v_fmac_f32_e32 v136, 0x3f317217, v135
	v_mov_b32_e32 v135, v136
	v_mul_f32_e32 v136, 0xbfb8aa3b, v48
	v_exp_f32_e32 v136, v136
	s_nop 0
	v_add_f32_e32 v136, 1.0, v136
	v_rcp_f32_e32 v136, v136
	s_nop 0
	v_fma_f32 v136, v136, v194, v167
	v_log_f32_e32 v136, v136
	s_nop 0
	v_mul_f32_e32 v137, 0x3f317217, v136
	v_fma_f32 v137, v136, s62, -v137
	v_fmac_f32_e32 v137, 0x3377d1cf, v136
	v_fmac_f32_e32 v137, 0x3f317217, v136
	v_mov_b32_e32 v136, v137
	v_mul_f32_e32 v137, 0xbfb8aa3b, v49
	v_exp_f32_e32 v137, v137
	s_nop 0
	v_add_f32_e32 v137, 1.0, v137
	v_rcp_f32_e32 v137, v137
	s_nop 0
	v_fma_f32 v137, v137, v196, v195
	v_cmp_gt_f32_e32 vcc, s63, v137
	s_nop 1
	v_cndmask_b32_e64 v153, 0, 32, vcc
	v_ldexp_f32 v137, v137, v153
	v_log_f32_e32 v137, v137
	s_nop 0
; __device__ __forceinline__ float sigm(float x) { return __builtin_amdgcn_rcpf(1.f + fexp(-x)); }
;   __device__ __forceinline__ void operator()(const AccT& acc, int pm, int pn, int wr, int wc, int fr, int fq) const {
;     ...
;       const int dir = seg - 1;
;       float* GF = (float*)(ws + OFF_GF);
;       const float* LB = (const float*)(ws + OFF_LB) + l * 1024 + dir * 512;
; #pragma unroll
;       for (int bj = 0; bj < 2; ++bj)
; #pragma unroll
;         for (int n = 0; n < 2; ++n) { const int c = cin + bj * 128 + n * 4; const f32x4 lb = *(const f32x4*)(LB + c);
; #pragma unroll
;           for (int ai = 0; ai < 2; ++ai)
; #pragma unroll
;             for (int m = 0; m < 4; ++m) { const f32x4 v = acc[ai][bj][m][n]; f32x4 o;
; #pragma unroll
;               for (int j = 0; j < 4; ++j) o[j] = __logf(fmaxf(lb[j], 1e-30f) + (1.f - lb[j]) * sigm(v[j]));
;               *(f32x4*)(GF + (size_t)(row0 + ai * 128 + m * 16) * 1024 + dir * 512 + c) = o; } }
	v_mul_f32_e32 v153, 0x3f317217, v137
	v_fma_f32 v153, v137, s62, -v153
	v_fmac_f32_e32 v153, 0x3377d1cf, v137
	v_fmac_f32_e32 v153, 0x3f317217, v137
	v_cmp_lt_f32_e64 s[0:1], |v137|, s94
	s_nop 1
	v_cndmask_b32_e64 v137, v137, v153, s[0:1]
	s_mov_b64 s[0:1], 0x90000
	v_lshl_add_u64 v[164:165], v[154:155], 0, s[0:1]
	s_mov_b32 s0, 0x90000
	v_cndmask_b32_e32 v153, 0, v186, vcc
	v_add_co_u32_e32 v168, vcc, s0, v154
	v_sub_f32_e32 v137, v137, v153
	s_nop 0
	v_addc_co_u32_e32 v169, vcc, 0, v155, vcc
	global_store_dwordx4 v[168:169], v[134:137], off
	s_nop 1
	v_mul_f32_e32 v134, 0xbfb8aa3b, v30
	v_exp_f32_e32 v134, v134
	s_nop 0
	v_add_f32_e32 v134, 1.0, v134
	v_rcp_f32_e32 v134, v134
	s_nop 0
	v_fma_f32 v134, v134, v198, v197
	v_log_f32_e32 v134, v134
	s_nop 0
	v_mul_f32_e32 v135, 0x3f317217, v134
	v_fma_f32 v135, v134, s62, -v135
	v_fmac_f32_e32 v135, 0x3377d1cf, v134
	v_fmac_f32_e32 v135, 0x3f317217, v134
	v_mov_b32_e32 v134, v135
	v_mul_f32_e32 v135, 0xbfb8aa3b, v31
	v_exp_f32_e32 v135, v135
	s_nop 0
	v_add_f32_e32 v135, 1.0, v135
	v_rcp_f32_e32 v135, v135
	s_nop 0
	v_fma_f32 v135, v135, v166, v151
	v_log_f32_e32 v135, v135
	s_nop 0
	v_mul_f32_e32 v136, 0x3f317217, v135
	v_fma_f32 v136, v135, s62, -v136
	v_fmac_f32_e32 v136, 0x3377d1cf, v135
	v_fmac_f32_e32 v136, 0x3f317217, v135
	v_mov_b32_e32 v135, v136
	v_mul_f32_e32 v136, 0xbfb8aa3b, v32
	v_exp_f32_e32 v136, v136
	s_nop 0
	v_add_f32_e32 v136, 1.0, v136
	v_rcp_f32_e32 v136, v136
	s_nop 0
	v_fma_f32 v136, v136, v194, v167
	v_log_f32_e32 v136, v136
	s_nop 0
	v_mul_f32_e32 v137, 0x3f317217, v136
	v_fma_f32 v137, v136, s62, -v137
	v_fmac_f32_e32 v137, 0x3377d1cf, v136
	v_fmac_f32_e32 v137, 0x3f317217, v136
	v_mov_b32_e32 v136, v137
	v_mul_f32_e32 v137, 0xbfb8aa3b, v33
	v_exp_f32_e32 v137, v137
	s_nop 0
	v_add_f32_e32 v137, 1.0, v137
	v_rcp_f32_e32 v137, v137
	s_nop 0
	v_fma_f32 v137, v137, v196, v195
	v_cmp_gt_f32_e32 vcc, s63, v137
	s_nop 1
	v_cndmask_b32_e64 v153, 0, 32, vcc
	v_ldexp_f32 v137, v137, v153
	v_log_f32_e32 v137, v137
	s_nop 0
	v_mul_f32_e32 v153, 0x3f317217, v137
	v_fma_f32 v153, v137, s62, -v153
	v_fmac_f32_e32 v153, 0x3377d1cf, v137
	v_fmac_f32_e32 v153, 0x3f317217, v137
	v_cmp_lt_f32_e64 s[0:1], |v137|, s94
	s_nop 1
	v_cndmask_b32_e64 v137, v137, v153, s[0:1]
	s_mov_b64 s[0:1], 0xa0000
	v_lshl_add_u64 v[168:169], v[154:155], 0, s[0:1]
	s_mov_b32 s0, 0xa0000
	v_cndmask_b32_e32 v153, 0, v186, vcc
	v_add_co_u32_e32 v200, vcc, s0, v154
	v_sub_f32_e32 v137, v137, v153
	s_nop 0
	v_addc_co_u32_e32 v201, vcc, 0, v155, vcc
	global_store_dwordx4 v[200:201], v[134:137], off
	v_sub_f32_e32 v153, 1.0, v132
	s_nop 0
	v_mul_f32_e32 v134, 0xbfb8aa3b, v14
	v_exp_f32_e32 v134, v134
	s_nop 0
	v_add_f32_e32 v134, 1.0, v134
	v_rcp_f32_e32 v134, v134
	s_nop 0
	v_fmac_f32_e32 v197, v134, v198
	v_log_f32_e32 v134, v197
	s_nop 0
	v_mul_f32_e32 v135, 0x3f317217, v134
	v_fma_f32 v135, v134, s62, -v135
	v_fmac_f32_e32 v135, 0x3377d1cf, v134
	v_fmac_f32_e32 v135, 0x3f317217, v134
	v_mov_b32_e32 v134, v135
	v_mul_f32_e32 v135, 0xbfb8aa3b, v15
	v_exp_f32_e32 v135, v135
	s_nop 0
	v_add_f32_e32 v135, 1.0, v135
	v_rcp_f32_e32 v135, v135
	s_nop 0
	v_fmac_f32_e32 v151, v135, v166
	v_log_f32_e32 v135, v151
	s_nop 0
	v_mul_f32_e32 v136, 0x3f317217, v135
	v_fma_f32 v136, v135, s62, -v136
	v_fmac_f32_e32 v136, 0x3377d1cf, v135
	v_fmac_f32_e32 v136, 0x3f317217, v135
	v_mov_b32_e32 v135, v136
	v_mul_f32_e32 v136, 0xbfb8aa3b, v16
	v_exp_f32_e32 v136, v136
	s_nop 0
	v_add_f32_e32 v136, 1.0, v136
	v_rcp_f32_e32 v136, v136
	s_nop 0
	v_fmac_f32_e32 v167, v136, v194
	v_log_f32_e32 v136, v167
	s_nop 0
	v_mul_f32_e32 v137, 0x3f317217, v136
	v_fma_f32 v137, v136, s62, -v137
	v_fmac_f32_e32 v137, 0x3377d1cf, v136
	v_fmac_f32_e32 v137, 0x3f317217, v136
	v_mov_b32_e32 v136, v137
	v_mul_f32_e32 v137, 0xbfb8aa3b, v17
	v_exp_f32_e32 v137, v137
	s_nop 0
	v_add_f32_e32 v137, 1.0, v137
	v_rcp_f32_e32 v137, v137
	s_nop 0
	v_fmac_f32_e32 v195, v137, v196
	v_cmp_gt_f32_e32 vcc, s63, v195
	s_nop 1
	v_cndmask_b32_e64 v137, 0, 32, vcc
	v_ldexp_f32 v137, v195, v137
	v_log_f32_e32 v137, v137
	s_nop 0
	v_mul_f32_e32 v151, 0x3f317217, v137
	v_fma_f32 v151, v137, s62, -v151
	v_fmac_f32_e32 v151, 0x3377d1cf, v137
	v_fmac_f32_e32 v151, 0x3f317217, v137
	v_cmp_lt_f32_e64 s[0:1], |v137|, s94
	s_nop 1
	v_cndmask_b32_e64 v137, v137, v151, s[0:1]
	s_mov_b64 s[0:1], 0xb0000
	v_lshl_add_u64 v[166:167], v[154:155], 0, s[0:1]
	s_mov_b32 s0, 0xb0000
	v_cndmask_b32_e32 v151, 0, v186, vcc
	v_add_co_u32_e32 v194, vcc, s0, v154
	v_sub_f32_e32 v137, v137, v151
	s_nop 0
	v_addc_co_u32_e32 v195, vcc, 0, v155, vcc
	global_store_dwordx4 v[194:195], v[134:137], off
	v_sub_f32_e32 v195, 1.0, v133
	s_nop 0
	v_max_f32_e32 v134, v130, v130
	v_sub_f32_e32 v135, 1.0, v130
	v_mul_f32_e32 v130, 0xbfb8aa3b, v122
	v_exp_f32_e32 v130, v130
	v_max_f32_e32 v134, 0xda24260, v134
	v_sub_f32_e32 v137, 1.0, v131
	v_add_f32_e32 v130, 1.0, v130
	v_rcp_f32_e32 v130, v130
	s_nop 0
	v_fma_f32 v130, v130, v135, v134
	v_log_f32_e32 v130, v130
	s_nop 0
	v_mul_f32_e32 v136, 0x3f317217, v130
	v_fma_f32 v136, v130, s62, -v136
	v_fmac_f32_e32 v136, 0x3377d1cf, v130
	v_fmac_f32_e32 v136, 0x3f317217, v130
	v_mov_b32_e32 v130, v136
	v_max_f32_e32 v136, v131, v131
	v_mul_f32_e32 v131, 0xbfb8aa3b, v123
	v_exp_f32_e32 v131, v131
	v_max_f32_e32 v136, 0xda24260, v136
	v_add_f32_e32 v131, 1.0, v131
	v_rcp_f32_e32 v131, v131
	s_nop 0
	v_fma_f32 v131, v131, v137, v136
	v_log_f32_e32 v131, v131
	s_nop 0
	v_mul_f32_e32 v151, 0x3f317217, v131
	v_fma_f32 v151, v131, s62, -v151
	v_fmac_f32_e32 v151, 0x3377d1cf, v131
	v_fmac_f32_e32 v151, 0x3f317217, v131
	v_mov_b32_e32 v131, v151
	v_max_f32_e32 v151, v132, v132
; __device__ __forceinline__ float sigm(float x) { return __builtin_amdgcn_rcpf(1.f + fexp(-x)); }
;   __device__ __forceinline__ void operator()(const AccT& acc, int pm, int pn, int wr, int wc, int fr, int fq) const {
;     ...
;       const int dir = seg - 1;
;       float* GF = (float*)(ws + OFF_GF);
;       const float* LB = (const float*)(ws + OFF_LB) + l * 1024 + dir * 512;
; #pragma unroll
;       for (int bj = 0; bj < 2; ++bj)
; #pragma unroll
;         for (int n = 0; n < 2; ++n) { const int c = cin + bj * 128 + n * 4; const f32x4 lb = *(const f32x4*)(LB + c);
; #pragma unroll
;           for (int ai = 0; ai < 2; ++ai)
; #pragma unroll
;             for (int m = 0; m < 4; ++m) { const f32x4 v = acc[ai][bj][m][n]; f32x4 o;
; #pragma unroll
;               for (int j = 0; j < 4; ++j) o[j] = __logf(fmaxf(lb[j], 1e-30f) + (1.f - lb[j]) * sigm(v[j]));
;               *(f32x4*)(GF + (size_t)(row0 + ai * 128 + m * 16) * 1024 + dir * 512 + c) = o; } }
	v_mul_f32_e32 v132, 0xbfb8aa3b, v124
	v_exp_f32_e32 v132, v132
	v_max_f32_e32 v151, 0xda24260, v151
	v_add_f32_e32 v132, 1.0, v132
	v_rcp_f32_e32 v132, v132
	s_nop 0
	v_fma_f32 v132, v132, v153, v151
	v_log_f32_e32 v132, v132
	s_nop 0
	v_mul_f32_e32 v194, 0x3f317217, v132
	v_fma_f32 v194, v132, s62, -v194
	v_fmac_f32_e32 v194, 0x3377d1cf, v132
	v_fmac_f32_e32 v194, 0x3f317217, v132
	v_mov_b32_e32 v132, v194
	v_max_f32_e32 v194, v133, v133
	v_mul_f32_e32 v133, 0xbfb8aa3b, v125
	v_exp_f32_e32 v133, v133
	v_max_f32_e32 v194, 0xda24260, v194
	v_add_f32_e32 v133, 1.0, v133
	v_rcp_f32_e32 v133, v133
	s_nop 0
	v_fma_f32 v133, v133, v195, v194
	v_log_f32_e32 v133, v133
	s_nop 0
	v_mul_f32_e32 v196, 0x3f317217, v133
	v_fma_f32 v196, v133, s62, -v196
	v_fmac_f32_e32 v196, 0x3377d1cf, v133
	v_fmac_f32_e32 v196, 0x3f317217, v133
	v_mov_b32_e32 v133, v196
	global_store_dwordx4 v[154:155], v[130:133], off offset:16
	s_nop 1
	v_mul_f32_e32 v130, 0xbfb8aa3b, v106
	v_exp_f32_e32 v130, v130
	s_nop 0
	v_add_f32_e32 v130, 1.0, v130
	v_rcp_f32_e32 v130, v130
	s_nop 0
	v_fma_f32 v130, v130, v135, v134
	v_log_f32_e32 v130, v130
	s_nop 0
	v_mul_f32_e32 v131, 0x3f317217, v130
	v_fma_f32 v131, v130, s62, -v131
	v_fmac_f32_e32 v131, 0x3377d1cf, v130
	v_fmac_f32_e32 v131, 0x3f317217, v130
	v_mov_b32_e32 v130, v131
	v_mul_f32_e32 v131, 0xbfb8aa3b, v107
	v_exp_f32_e32 v131, v131
	s_nop 0
	v_add_f32_e32 v131, 1.0, v131
	v_rcp_f32_e32 v131, v131
	s_nop 0
	v_fma_f32 v131, v131, v137, v136
	v_log_f32_e32 v131, v131
	s_nop 0
	v_mul_f32_e32 v132, 0x3f317217, v131
	v_fma_f32 v132, v131, s62, -v132
	v_fmac_f32_e32 v132, 0x3377d1cf, v131
	v_fmac_f32_e32 v132, 0x3f317217, v131
	v_mov_b32_e32 v131, v132
	v_mul_f32_e32 v132, 0xbfb8aa3b, v108
	v_exp_f32_e32 v132, v132
	s_nop 0
	v_add_f32_e32 v132, 1.0, v132
	v_rcp_f32_e32 v132, v132
	s_nop 0
	v_fma_f32 v132, v132, v153, v151
	v_log_f32_e32 v132, v132
	s_nop 0
	v_mul_f32_e32 v133, 0x3f317217, v132
	v_fma_f32 v133, v132, s62, -v133
	v_fmac_f32_e32 v133, 0x3377d1cf, v132
	v_fmac_f32_e32 v133, 0x3f317217, v132
	v_mov_b32_e32 v132, v133
	v_mul_f32_e32 v133, 0xbfb8aa3b, v109
	v_exp_f32_e32 v133, v133
	s_nop 0
	v_add_f32_e32 v133, 1.0, v133
	v_rcp_f32_e32 v133, v133
	s_nop 0
	v_fma_f32 v133, v133, v195, v194
	v_log_f32_e32 v133, v133
	s_nop 0
	v_mul_f32_e32 v196, 0x3f317217, v133
	v_fma_f32 v196, v133, s62, -v196
	v_fmac_f32_e32 v196, 0x3377d1cf, v133
	v_fmac_f32_e32 v196, 0x3f317217, v133
	v_mov_b32_e32 v133, v196
	global_store_dwordx4 v[156:157], v[130:133], off offset:16
	s_nop 1
	v_mul_f32_e32 v130, 0xbfb8aa3b, v90
	v_exp_f32_e32 v130, v130
	s_nop 0
	v_add_f32_e32 v130, 1.0, v130
	v_rcp_f32_e32 v130, v130
	s_nop 0
	v_fma_f32 v130, v130, v135, v134
	v_log_f32_e32 v130, v130
	s_nop 0
	v_mul_f32_e32 v131, 0x3f317217, v130
	v_fma_f32 v131, v130, s62, -v131
	v_fmac_f32_e32 v131, 0x3377d1cf, v130
	v_fmac_f32_e32 v131, 0x3f317217, v130
	v_mov_b32_e32 v130, v131
	v_mul_f32_e32 v131, 0xbfb8aa3b, v91
	v_exp_f32_e32 v131, v131
	s_nop 0
	v_add_f32_e32 v131, 1.0, v131
	v_rcp_f32_e32 v131, v131
	s_nop 0
	v_fma_f32 v131, v131, v137, v136
	v_log_f32_e32 v131, v131
	s_nop 0
	v_mul_f32_e32 v132, 0x3f317217, v131
	v_fma_f32 v132, v131, s62, -v132
	v_fmac_f32_e32 v132, 0x3377d1cf, v131
	v_fmac_f32_e32 v132, 0x3f317217, v131
	v_mov_b32_e32 v131, v132
	v_mul_f32_e32 v132, 0xbfb8aa3b, v92
	v_exp_f32_e32 v132, v132
	s_nop 0
	v_add_f32_e32 v132, 1.0, v132
	v_rcp_f32_e32 v132, v132
	s_nop 0
	v_fma_f32 v132, v132, v153, v151
	v_log_f32_e32 v132, v132
	s_nop 0
	v_mul_f32_e32 v133, 0x3f317217, v132
	v_fma_f32 v133, v132, s62, -v133
	v_fmac_f32_e32 v133, 0x3377d1cf, v132
	v_fmac_f32_e32 v133, 0x3f317217, v132
	v_mov_b32_e32 v132, v133
	v_mul_f32_e32 v133, 0xbfb8aa3b, v93
	v_exp_f32_e32 v133, v133
	s_nop 0
	v_add_f32_e32 v133, 1.0, v133
	v_rcp_f32_e32 v133, v133
	s_nop 0
	v_fma_f32 v133, v133, v195, v194
	v_log_f32_e32 v133, v133
	s_nop 0
	v_mul_f32_e32 v196, 0x3f317217, v133
	v_fma_f32 v196, v133, s62, -v196
	v_fmac_f32_e32 v196, 0x3377d1cf, v133
	v_fmac_f32_e32 v196, 0x3f317217, v133
	v_mov_b32_e32 v133, v196
	global_store_dwordx4 v[158:159], v[130:133], off offset:16
	s_nop 1
	v_mul_f32_e32 v130, 0xbfb8aa3b, v74
	v_exp_f32_e32 v130, v130
	s_nop 0
	v_add_f32_e32 v130, 1.0, v130
	v_rcp_f32_e32 v130, v130
	s_nop 0
	v_fma_f32 v130, v130, v135, v134
	v_log_f32_e32 v130, v130
	s_nop 0
	v_mul_f32_e32 v131, 0x3f317217, v130
	v_fma_f32 v131, v130, s62, -v131
	v_fmac_f32_e32 v131, 0x3377d1cf, v130
	v_fmac_f32_e32 v131, 0x3f317217, v130
	v_mov_b32_e32 v130, v131
	v_mul_f32_e32 v131, 0xbfb8aa3b, v75
	v_exp_f32_e32 v131, v131
	s_nop 0
	v_add_f32_e32 v131, 1.0, v131
	v_rcp_f32_e32 v131, v131
	s_nop 0
	v_fma_f32 v131, v131, v137, v136
	v_log_f32_e32 v131, v131
	s_nop 0
	v_mul_f32_e32 v132, 0x3f317217, v131
	v_fma_f32 v132, v131, s62, -v132
	v_fmac_f32_e32 v132, 0x3377d1cf, v131
	v_fmac_f32_e32 v132, 0x3f317217, v131
	v_mov_b32_e32 v131, v132
	v_mul_f32_e32 v132, 0xbfb8aa3b, v76
	v_exp_f32_e32 v132, v132
	s_nop 0
	v_add_f32_e32 v132, 1.0, v132
	v_rcp_f32_e32 v132, v132
	s_nop 0
	v_fma_f32 v132, v132, v153, v151
	v_log_f32_e32 v132, v132
	s_nop 0
	v_mul_f32_e32 v133, 0x3f317217, v132
	v_fma_f32 v133, v132, s62, -v133
	v_fmac_f32_e32 v133, 0x3377d1cf, v132
	v_fmac_f32_e32 v133, 0x3f317217, v132
	v_mov_b32_e32 v132, v133
	v_mul_f32_e32 v133, 0xbfb8aa3b, v77
	v_exp_f32_e32 v133, v133
	s_nop 0
	v_add_f32_e32 v133, 1.0, v133
	v_rcp_f32_e32 v133, v133
	s_nop 0
	v_fma_f32 v133, v133, v195, v194
	v_log_f32_e32 v133, v133
	s_nop 0
	v_mul_f32_e32 v196, 0x3f317217, v133
	v_fma_f32 v196, v133, s62, -v196
	v_fmac_f32_e32 v196, 0x3377d1cf, v133
	v_fmac_f32_e32 v196, 0x3f317217, v133
; __device__ __forceinline__ float sigm(float x) { return __builtin_amdgcn_rcpf(1.f + fexp(-x)); }
;   __device__ __forceinline__ void operator()(const AccT& acc, int pm, int pn, int wr, int wc, int fr, int fq) const {
;     ...
;       const int dir = seg - 1;
;       float* GF = (float*)(ws + OFF_GF);
;       const float* LB = (const float*)(ws + OFF_LB) + l * 1024 + dir * 512;
; #pragma unroll
;       for (int bj = 0; bj < 2; ++bj)
; #pragma unroll
;         for (int n = 0; n < 2; ++n) { const int c = cin + bj * 128 + n * 4; const f32x4 lb = *(const f32x4*)(LB + c);
; #pragma unroll
;           for (int ai = 0; ai < 2; ++ai)
; #pragma unroll
;             for (int m = 0; m < 4; ++m) { const f32x4 v = acc[ai][bj][m][n]; f32x4 o;
; #pragma unroll
;               for (int j = 0; j < 4; ++j) o[j] = __logf(fmaxf(lb[j], 1e-30f) + (1.f - lb[j]) * sigm(v[j]));
;               *(f32x4*)(GF + (size_t)(row0 + ai * 128 + m * 16) * 1024 + dir * 512 + c) = o; } }
	v_mov_b32_e32 v133, v196
	global_store_dwordx4 v[160:161], v[130:133], off offset:16
	s_nop 1
	v_mul_f32_e32 v130, 0xbfb8aa3b, v58
	v_exp_f32_e32 v130, v130
	s_nop 0
	v_add_f32_e32 v130, 1.0, v130
	v_rcp_f32_e32 v130, v130
	s_nop 0
	v_fma_f32 v130, v130, v135, v134
	v_log_f32_e32 v130, v130
	s_nop 0
	v_mul_f32_e32 v131, 0x3f317217, v130
	v_fma_f32 v131, v130, s62, -v131
	v_fmac_f32_e32 v131, 0x3377d1cf, v130
	v_fmac_f32_e32 v131, 0x3f317217, v130
	v_mov_b32_e32 v130, v131
	v_mul_f32_e32 v131, 0xbfb8aa3b, v59
	v_exp_f32_e32 v131, v131
	s_nop 0
	v_add_f32_e32 v131, 1.0, v131
	v_rcp_f32_e32 v131, v131
	s_nop 0
	v_fma_f32 v131, v131, v137, v136
	v_log_f32_e32 v131, v131
	s_nop 0
	v_mul_f32_e32 v132, 0x3f317217, v131
	v_fma_f32 v132, v131, s62, -v132
	v_fmac_f32_e32 v132, 0x3377d1cf, v131
	v_fmac_f32_e32 v132, 0x3f317217, v131
	v_mov_b32_e32 v131, v132
	v_mul_f32_e32 v132, 0xbfb8aa3b, v60
	v_exp_f32_e32 v132, v132
	s_nop 0
	v_add_f32_e32 v132, 1.0, v132
	v_rcp_f32_e32 v132, v132
	s_nop 0
	v_fma_f32 v132, v132, v153, v151
	v_log_f32_e32 v132, v132
	s_nop 0
	v_mul_f32_e32 v133, 0x3f317217, v132
	v_fma_f32 v133, v132, s62, -v133
	v_fmac_f32_e32 v133, 0x3377d1cf, v132
	v_fmac_f32_e32 v133, 0x3f317217, v132
	v_mov_b32_e32 v132, v133
	v_mul_f32_e32 v133, 0xbfb8aa3b, v61
	v_exp_f32_e32 v133, v133
	s_nop 0
	v_add_f32_e32 v133, 1.0, v133
	v_rcp_f32_e32 v133, v133
	s_nop 0
	v_fma_f32 v133, v133, v195, v194
	v_log_f32_e32 v133, v133
	s_nop 0
	v_mul_f32_e32 v196, 0x3f317217, v133
	v_fma_f32 v196, v133, s62, -v196
	v_fmac_f32_e32 v196, 0x3377d1cf, v133
	v_fmac_f32_e32 v196, 0x3f317217, v133
	v_mov_b32_e32 v133, v196
	global_store_dwordx4 v[162:163], v[130:133], off offset:16
	s_nop 1
	v_mul_f32_e32 v130, 0xbfb8aa3b, v42
	v_exp_f32_e32 v130, v130
	s_nop 0
	v_add_f32_e32 v130, 1.0, v130
	v_rcp_f32_e32 v130, v130
	s_nop 0
	v_fma_f32 v130, v130, v135, v134
	v_log_f32_e32 v130, v130
	s_nop 0
	v_mul_f32_e32 v131, 0x3f317217, v130
	v_fma_f32 v131, v130, s62, -v131
	v_fmac_f32_e32 v131, 0x3377d1cf, v130
	v_fmac_f32_e32 v131, 0x3f317217, v130
	v_mov_b32_e32 v130, v131
	v_mul_f32_e32 v131, 0xbfb8aa3b, v43
	v_exp_f32_e32 v131, v131
	s_nop 0
	v_add_f32_e32 v131, 1.0, v131
	v_rcp_f32_e32 v131, v131
	s_nop 0
	v_fma_f32 v131, v131, v137, v136
	v_log_f32_e32 v131, v131
	s_nop 0
	v_mul_f32_e32 v132, 0x3f317217, v131
	v_fma_f32 v132, v131, s62, -v132
	v_fmac_f32_e32 v132, 0x3377d1cf, v131
	v_fmac_f32_e32 v132, 0x3f317217, v131
	v_mov_b32_e32 v131, v132
	v_mul_f32_e32 v132, 0xbfb8aa3b, v44
	v_exp_f32_e32 v132, v132
	s_nop 0
	v_add_f32_e32 v132, 1.0, v132
	v_rcp_f32_e32 v132, v132
	s_nop 0
	v_fma_f32 v132, v132, v153, v151
	v_log_f32_e32 v132, v132
	s_nop 0
	v_mul_f32_e32 v133, 0x3f317217, v132
	v_fma_f32 v133, v132, s62, -v133
	v_fmac_f32_e32 v133, 0x3377d1cf, v132
	v_fmac_f32_e32 v133, 0x3f317217, v132
	v_mov_b32_e32 v132, v133
	v_mul_f32_e32 v133, 0xbfb8aa3b, v45
	v_exp_f32_e32 v133, v133
	s_nop 0
	v_add_f32_e32 v133, 1.0, v133
	v_rcp_f32_e32 v133, v133
	s_nop 0
	v_fma_f32 v133, v133, v195, v194
	v_log_f32_e32 v133, v133
	s_nop 0
	v_mul_f32_e32 v196, 0x3f317217, v133
	v_fma_f32 v196, v133, s62, -v196
	v_fmac_f32_e32 v196, 0x3377d1cf, v133
	v_fmac_f32_e32 v196, 0x3f317217, v133
	v_mov_b32_e32 v133, v196
	global_store_dwordx4 v[164:165], v[130:133], off offset:16
	s_nop 1
	v_mul_f32_e32 v130, 0xbfb8aa3b, v26
	v_exp_f32_e32 v130, v130
	s_nop 0
	v_add_f32_e32 v130, 1.0, v130
	v_rcp_f32_e32 v130, v130
	s_nop 0
	v_fma_f32 v130, v130, v135, v134
	v_log_f32_e32 v130, v130
	s_nop 0
	v_mul_f32_e32 v131, 0x3f317217, v130
	v_fma_f32 v131, v130, s62, -v131
	v_fmac_f32_e32 v131, 0x3377d1cf, v130
	v_fmac_f32_e32 v131, 0x3f317217, v130
	v_mov_b32_e32 v130, v131
	v_mul_f32_e32 v131, 0xbfb8aa3b, v27
	v_exp_f32_e32 v131, v131
	s_nop 0
	v_add_f32_e32 v131, 1.0, v131
	v_rcp_f32_e32 v131, v131
	s_nop 0
	v_fma_f32 v131, v131, v137, v136
	v_log_f32_e32 v131, v131
	s_nop 0
	v_mul_f32_e32 v132, 0x3f317217, v131
	v_fma_f32 v132, v131, s62, -v132
	v_fmac_f32_e32 v132, 0x3377d1cf, v131
	v_fmac_f32_e32 v132, 0x3f317217, v131
	v_mov_b32_e32 v131, v132
	v_mul_f32_e32 v132, 0xbfb8aa3b, v28
	v_exp_f32_e32 v132, v132
	s_nop 0
	v_add_f32_e32 v132, 1.0, v132
	v_rcp_f32_e32 v132, v132
	s_nop 0
	v_fma_f32 v132, v132, v153, v151
	v_log_f32_e32 v132, v132
	s_nop 0
	v_mul_f32_e32 v133, 0x3f317217, v132
	v_fma_f32 v133, v132, s62, -v133
	v_fmac_f32_e32 v133, 0x3377d1cf, v132
	v_fmac_f32_e32 v133, 0x3f317217, v132
	v_mov_b32_e32 v132, v133
	v_mul_f32_e32 v133, 0xbfb8aa3b, v29
	v_exp_f32_e32 v133, v133
	s_nop 0
	v_add_f32_e32 v133, 1.0, v133
	v_rcp_f32_e32 v133, v133
	s_nop 0
	v_fma_f32 v133, v133, v195, v194
	v_log_f32_e32 v133, v133
	s_nop 0
	v_mul_f32_e32 v196, 0x3f317217, v133
	v_fma_f32 v196, v133, s62, -v196
	v_fmac_f32_e32 v196, 0x3377d1cf, v133
	v_fmac_f32_e32 v196, 0x3f317217, v133
	v_mov_b32_e32 v133, v196
	global_store_dwordx4 v[168:169], v[130:133], off offset:16
	s_nop 1
	v_mul_f32_e32 v130, 0xbfb8aa3b, v10
	v_exp_f32_e32 v130, v130
	s_nop 0
	v_add_f32_e32 v130, 1.0, v130
	v_rcp_f32_e32 v130, v130
	s_nop 0
	v_fmac_f32_e32 v134, v130, v135
	v_log_f32_e32 v130, v134
	s_nop 0
	v_mul_f32_e32 v131, 0x3f317217, v130
	v_fma_f32 v131, v130, s62, -v131
	v_fmac_f32_e32 v131, 0x3377d1cf, v130
	v_fmac_f32_e32 v131, 0x3f317217, v130
	v_mov_b32_e32 v130, v131
	v_mul_f32_e32 v131, 0xbfb8aa3b, v11
	v_exp_f32_e32 v131, v131
	s_nop 0
	v_add_f32_e32 v131, 1.0, v131
	v_rcp_f32_e32 v131, v131
	s_nop 0
	v_fmac_f32_e32 v136, v131, v137
	v_log_f32_e32 v131, v136
	s_nop 0
	v_mul_f32_e32 v132, 0x3f317217, v131
	v_fma_f32 v132, v131, s62, -v132
	v_fmac_f32_e32 v132, 0x3377d1cf, v131
	v_fmac_f32_e32 v132, 0x3f317217, v131
	v_mov_b32_e32 v131, v132
	v_mul_f32_e32 v132, 0xbfb8aa3b, v12
	v_exp_f32_e32 v132, v132
	s_nop 0
	v_add_f32_e32 v132, 1.0, v132
	v_rcp_f32_e32 v132, v132
	s_nop 0
	v_fmac_f32_e32 v151, v132, v153
	v_log_f32_e32 v132, v151
	s_nop 0
	v_mul_f32_e32 v133, 0x3f317217, v132
	v_fma_f32 v133, v132, s62, -v133
	v_fmac_f32_e32 v133, 0x3377d1cf, v132
	v_fmac_f32_e32 v133, 0x3f317217, v132
	v_mov_b32_e32 v132, v133
	v_mul_f32_e32 v133, 0xbfb8aa3b, v13
	v_exp_f32_e32 v133, v133
	s_nop 0
	v_add_f32_e32 v133, 1.0, v133
	v_rcp_f32_e32 v133, v133
	s_nop 0
	v_fmac_f32_e32 v194, v133, v195
	v_log_f32_e32 v133, v194
	s_nop 0
	v_mul_f32_e32 v134, 0x3f317217, v133
	v_fma_f32 v134, v133, s62, -v134
	v_fmac_f32_e32 v134, 0x3377d1cf, v133
	v_fmac_f32_e32 v134, 0x3f317217, v133
	v_mov_b32_e32 v133, v134
	global_store_dwordx4 v[166:167], v[130:133], off offset:16
	global_load_dwordx4 v[130:133], v0, s[6:7] offset:528
	s_nop 0
	global_load_dwordx4 v[134:137], v0, s[6:7] offset:512
	s_waitcnt vmcnt(0)
; __device__ __forceinline__ float sigm(float x) { return __builtin_amdgcn_rcpf(1.f + fexp(-x)); }
;   __device__ __forceinline__ void operator()(const AccT& acc, int pm, int pn, int wr, int wc, int fr, int fq) const {
;     ...
;       const int dir = seg - 1;
;       float* GF = (float*)(ws + OFF_GF);
;       const float* LB = (const float*)(ws + OFF_LB) + l * 1024 + dir * 512;
; #pragma unroll
;       for (int bj = 0; bj < 2; ++bj)
; #pragma unroll
;         for (int n = 0; n < 2; ++n) { const int c = cin + bj * 128 + n * 4; const f32x4 lb = *(const f32x4*)(LB + c);
; #pragma unroll
;           for (int ai = 0; ai < 2; ++ai)
; #pragma unroll
;             for (int m = 0; m < 4; ++m) { const f32x4 v = acc[ai][bj][m][n]; f32x4 o;
; #pragma unroll
;               for (int j = 0; j < 4; ++j) o[j] = __logf(fmaxf(lb[j], 1e-30f) + (1.f - lb[j]) * sigm(v[j]));
;               *(f32x4*)(GF + (size_t)(row0 + ai * 128 + m * 16) * 1024 + dir * 512 + c) = o; } }
	v_max_f32_e32 v0, v134, v134
	v_sub_f32_e32 v151, 1.0, v134
	v_mul_f32_e32 v134, 0xbfb8aa3b, v118
	v_exp_f32_e32 v134, v134
	v_max_f32_e32 v0, 0xda24260, v0
	v_sub_f32_e32 v194, 1.0, v135
	v_sub_f32_e32 v196, 1.0, v136
	v_add_f32_e32 v134, 1.0, v134
	v_rcp_f32_e32 v134, v134
	v_sub_f32_e32 v198, 1.0, v137
	v_fma_f32 v134, v134, v151, v0
	v_log_f32_e32 v134, v134
	s_nop 0
	v_mul_f32_e32 v153, 0x3f317217, v134
	v_fma_f32 v153, v134, s62, -v153
	v_fmac_f32_e32 v153, 0x3377d1cf, v134
	v_fmac_f32_e32 v153, 0x3f317217, v134
	v_mov_b32_e32 v134, v153
	v_max_f32_e32 v153, v135, v135
	v_mul_f32_e32 v135, 0xbfb8aa3b, v119
	v_exp_f32_e32 v135, v135
	v_max_f32_e32 v153, 0xda24260, v153
	v_add_f32_e32 v135, 1.0, v135
	v_rcp_f32_e32 v135, v135
	s_nop 0
	v_fma_f32 v135, v135, v194, v153
	v_log_f32_e32 v135, v135
	s_nop 0
	v_mul_f32_e32 v195, 0x3f317217, v135
	v_fma_f32 v195, v135, s62, -v195
	v_fmac_f32_e32 v195, 0x3377d1cf, v135
	v_fmac_f32_e32 v195, 0x3f317217, v135
	v_mov_b32_e32 v135, v195
	v_max_f32_e32 v195, v136, v136
	v_mul_f32_e32 v136, 0xbfb8aa3b, v120
	v_exp_f32_e32 v136, v136
	v_max_f32_e32 v195, 0xda24260, v195
	v_add_f32_e32 v136, 1.0, v136
	v_rcp_f32_e32 v136, v136
	s_nop 0
	v_fma_f32 v136, v136, v196, v195
	v_log_f32_e32 v136, v136
	s_nop 0
	v_mul_f32_e32 v197, 0x3f317217, v136
	v_fma_f32 v197, v136, s62, -v197
	v_fmac_f32_e32 v197, 0x3377d1cf, v136
	v_fmac_f32_e32 v197, 0x3f317217, v136
	v_mov_b32_e32 v136, v197
	v_max_f32_e32 v197, v137, v137
	v_mul_f32_e32 v137, 0xbfb8aa3b, v121
	v_exp_f32_e32 v137, v137
	v_max_f32_e32 v197, 0xda24260, v197
	v_add_f32_e32 v137, 1.0, v137
	v_rcp_f32_e32 v137, v137
	s_nop 0
	v_fma_f32 v137, v137, v198, v197
	v_log_f32_e32 v137, v137
	s_nop 0
	v_mul_f32_e32 v199, 0x3f317217, v137
	v_fma_f32 v199, v137, s62, -v199
	v_fmac_f32_e32 v199, 0x3377d1cf, v137
	v_fmac_f32_e32 v199, 0x3f317217, v137
	v_mov_b32_e32 v137, v199
	global_store_dwordx4 v[154:155], v[134:137], off offset:512
	s_nop 1
	v_mul_f32_e32 v134, 0xbfb8aa3b, v102
	v_exp_f32_e32 v134, v134
	s_nop 0
	v_add_f32_e32 v134, 1.0, v134
	v_rcp_f32_e32 v134, v134
	s_nop 0
	v_fma_f32 v134, v134, v151, v0
	v_log_f32_e32 v134, v134
	s_nop 0
	v_mul_f32_e32 v135, 0x3f317217, v134
	v_fma_f32 v135, v134, s62, -v135
	v_fmac_f32_e32 v135, 0x3377d1cf, v134
	v_fmac_f32_e32 v135, 0x3f317217, v134
	v_mov_b32_e32 v134, v135
	v_mul_f32_e32 v135, 0xbfb8aa3b, v103
	v_exp_f32_e32 v135, v135
	s_nop 0
	v_add_f32_e32 v135, 1.0, v135
	v_rcp_f32_e32 v135, v135
	s_nop 0
	v_fma_f32 v135, v135, v194, v153
	v_log_f32_e32 v135, v135
	s_nop 0
	v_mul_f32_e32 v136, 0x3f317217, v135
	v_fma_f32 v136, v135, s62, -v136
	v_fmac_f32_e32 v136, 0x3377d1cf, v135
	v_fmac_f32_e32 v136, 0x3f317217, v135
	v_mov_b32_e32 v135, v136
	v_mul_f32_e32 v136, 0xbfb8aa3b, v104
	v_exp_f32_e32 v136, v136
	s_nop 0
	v_add_f32_e32 v136, 1.0, v136
	v_rcp_f32_e32 v136, v136
	s_nop 0
	v_fma_f32 v136, v136, v196, v195
	v_log_f32_e32 v136, v136
	s_nop 0
	v_mul_f32_e32 v137, 0x3f317217, v136
	v_fma_f32 v137, v136, s62, -v137
	v_fmac_f32_e32 v137, 0x3377d1cf, v136
	v_fmac_f32_e32 v137, 0x3f317217, v136
	v_mov_b32_e32 v136, v137
	v_mul_f32_e32 v137, 0xbfb8aa3b, v105
	v_exp_f32_e32 v137, v137
	s_nop 0
	v_add_f32_e32 v137, 1.0, v137
	v_rcp_f32_e32 v137, v137
	s_nop 0
	v_fma_f32 v137, v137, v198, v197
	v_log_f32_e32 v137, v137
	s_nop 0
	v_mul_f32_e32 v199, 0x3f317217, v137
	v_fma_f32 v199, v137, s62, -v199
	v_fmac_f32_e32 v199, 0x3377d1cf, v137
	v_fmac_f32_e32 v199, 0x3f317217, v137
	v_mov_b32_e32 v137, v199
	global_store_dwordx4 v[156:157], v[134:137], off offset:512
	s_nop 1
	v_mul_f32_e32 v134, 0xbfb8aa3b, v86
	v_exp_f32_e32 v134, v134
	s_nop 0
	v_add_f32_e32 v134, 1.0, v134
	v_rcp_f32_e32 v134, v134
	s_nop 0
	v_fma_f32 v134, v134, v151, v0
	v_log_f32_e32 v134, v134
	s_nop 0
	v_mul_f32_e32 v135, 0x3f317217, v134
	v_fma_f32 v135, v134, s62, -v135
	v_fmac_f32_e32 v135, 0x3377d1cf, v134
	v_fmac_f32_e32 v135, 0x3f317217, v134
	v_mov_b32_e32 v134, v135
	v_mul_f32_e32 v135, 0xbfb8aa3b, v87
	v_exp_f32_e32 v135, v135
	s_nop 0
	v_add_f32_e32 v135, 1.0, v135
	v_rcp_f32_e32 v135, v135
	s_nop 0
	v_fma_f32 v135, v135, v194, v153
	v_log_f32_e32 v135, v135
	s_nop 0
	v_mul_f32_e32 v136, 0x3f317217, v135
	v_fma_f32 v136, v135, s62, -v136
	v_fmac_f32_e32 v136, 0x3377d1cf, v135
	v_fmac_f32_e32 v136, 0x3f317217, v135
	v_mov_b32_e32 v135, v136
	v_mul_f32_e32 v136, 0xbfb8aa3b, v88
	v_exp_f32_e32 v136, v136
	s_nop 0
	v_add_f32_e32 v136, 1.0, v136
	v_rcp_f32_e32 v136, v136
	s_nop 0
	v_fma_f32 v136, v136, v196, v195
	v_log_f32_e32 v136, v136
	s_nop 0
	v_mul_f32_e32 v137, 0x3f317217, v136
	v_fma_f32 v137, v136, s62, -v137
	v_fmac_f32_e32 v137, 0x3377d1cf, v136
	v_fmac_f32_e32 v137, 0x3f317217, v136
	v_mov_b32_e32 v136, v137
	v_mul_f32_e32 v137, 0xbfb8aa3b, v89
	v_exp_f32_e32 v137, v137
	s_nop 0
	v_add_f32_e32 v137, 1.0, v137
	v_rcp_f32_e32 v137, v137
	s_nop 0
	v_fma_f32 v137, v137, v198, v197
	v_log_f32_e32 v137, v137
	s_nop 0
	v_mul_f32_e32 v199, 0x3f317217, v137
	v_fma_f32 v199, v137, s62, -v199
	v_fmac_f32_e32 v199, 0x3377d1cf, v137
	v_fmac_f32_e32 v199, 0x3f317217, v137
	v_mov_b32_e32 v137, v199
	global_store_dwordx4 v[158:159], v[134:137], off offset:512
	s_nop 1
	v_mul_f32_e32 v134, 0xbfb8aa3b, v70
	v_exp_f32_e32 v134, v134
	s_nop 0
	v_add_f32_e32 v134, 1.0, v134
	v_rcp_f32_e32 v134, v134
	s_nop 0
	v_fma_f32 v134, v134, v151, v0
	v_log_f32_e32 v134, v134
	s_nop 0
	v_mul_f32_e32 v135, 0x3f317217, v134
	v_fma_f32 v135, v134, s62, -v135
	v_fmac_f32_e32 v135, 0x3377d1cf, v134
	v_fmac_f32_e32 v135, 0x3f317217, v134
	v_mov_b32_e32 v134, v135
	v_mul_f32_e32 v135, 0xbfb8aa3b, v71
	v_exp_f32_e32 v135, v135
	s_nop 0
	v_add_f32_e32 v135, 1.0, v135
; __device__ __forceinline__ float sigm(float x) { return __builtin_amdgcn_rcpf(1.f + fexp(-x)); }
;   __device__ __forceinline__ void operator()(const AccT& acc, int pm, int pn, int wr, int wc, int fr, int fq) const {
;     ...
;       const int dir = seg - 1;
;       float* GF = (float*)(ws + OFF_GF);
;       const float* LB = (const float*)(ws + OFF_LB) + l * 1024 + dir * 512;
; #pragma unroll
;       for (int bj = 0; bj < 2; ++bj)
; #pragma unroll
;         for (int n = 0; n < 2; ++n) { const int c = cin + bj * 128 + n * 4; const f32x4 lb = *(const f32x4*)(LB + c);
; #pragma unroll
;           for (int ai = 0; ai < 2; ++ai)
; #pragma unroll
;             for (int m = 0; m < 4; ++m) { const f32x4 v = acc[ai][bj][m][n]; f32x4 o;
; #pragma unroll
;               for (int j = 0; j < 4; ++j) o[j] = __logf(fmaxf(lb[j], 1e-30f) + (1.f - lb[j]) * sigm(v[j]));
;               *(f32x4*)(GF + (size_t)(row0 + ai * 128 + m * 16) * 1024 + dir * 512 + c) = o; } }
	v_rcp_f32_e32 v135, v135
	s_nop 0
	v_fma_f32 v135, v135, v194, v153
	v_log_f32_e32 v135, v135
	s_nop 0
	v_mul_f32_e32 v136, 0x3f317217, v135
	v_fma_f32 v136, v135, s62, -v136
	v_fmac_f32_e32 v136, 0x3377d1cf, v135
	v_fmac_f32_e32 v136, 0x3f317217, v135
	v_mov_b32_e32 v135, v136
	v_mul_f32_e32 v136, 0xbfb8aa3b, v72
	v_exp_f32_e32 v136, v136
	s_nop 0
	v_add_f32_e32 v136, 1.0, v136
	v_rcp_f32_e32 v136, v136
	s_nop 0
	v_fma_f32 v136, v136, v196, v195
	v_log_f32_e32 v136, v136
	s_nop 0
	v_mul_f32_e32 v137, 0x3f317217, v136
	v_fma_f32 v137, v136, s62, -v137
	v_fmac_f32_e32 v137, 0x3377d1cf, v136
	v_fmac_f32_e32 v137, 0x3f317217, v136
	v_mov_b32_e32 v136, v137
	v_mul_f32_e32 v137, 0xbfb8aa3b, v73
	v_exp_f32_e32 v137, v137
	s_nop 0
	v_add_f32_e32 v137, 1.0, v137
	v_rcp_f32_e32 v137, v137
	s_nop 0
	v_fma_f32 v137, v137, v198, v197
	v_log_f32_e32 v137, v137
	s_nop 0
	v_mul_f32_e32 v199, 0x3f317217, v137
	v_fma_f32 v199, v137, s62, -v199
	v_fmac_f32_e32 v199, 0x3377d1cf, v137
	v_fmac_f32_e32 v199, 0x3f317217, v137
	v_mov_b32_e32 v137, v199
	global_store_dwordx4 v[160:161], v[134:137], off offset:512
	s_nop 1
	v_mul_f32_e32 v134, 0xbfb8aa3b, v54
	v_exp_f32_e32 v134, v134
	s_nop 0
	v_add_f32_e32 v134, 1.0, v134
	v_rcp_f32_e32 v134, v134
	s_nop 0
	v_fma_f32 v134, v134, v151, v0
	v_log_f32_e32 v134, v134
	s_nop 0
	v_mul_f32_e32 v135, 0x3f317217, v134
	v_fma_f32 v135, v134, s62, -v135
	v_fmac_f32_e32 v135, 0x3377d1cf, v134
	v_fmac_f32_e32 v135, 0x3f317217, v134
	v_mov_b32_e32 v134, v135
	v_mul_f32_e32 v135, 0xbfb8aa3b, v55
	v_exp_f32_e32 v135, v135
	s_nop 0
	v_add_f32_e32 v135, 1.0, v135
	v_rcp_f32_e32 v135, v135
	s_nop 0
	v_fma_f32 v135, v135, v194, v153
	v_log_f32_e32 v135, v135
	s_nop 0
	v_mul_f32_e32 v136, 0x3f317217, v135
	v_fma_f32 v136, v135, s62, -v136
	v_fmac_f32_e32 v136, 0x3377d1cf, v135
	v_fmac_f32_e32 v136, 0x3f317217, v135
	v_mov_b32_e32 v135, v136
	v_mul_f32_e32 v136, 0xbfb8aa3b, v56
	v_exp_f32_e32 v136, v136
	s_nop 0
	v_add_f32_e32 v136, 1.0, v136
	v_rcp_f32_e32 v136, v136
	s_nop 0
	v_fma_f32 v136, v136, v196, v195
	v_log_f32_e32 v136, v136
	s_nop 0
	v_mul_f32_e32 v137, 0x3f317217, v136
	v_fma_f32 v137, v136, s62, -v137
	v_fmac_f32_e32 v137, 0x3377d1cf, v136
	v_fmac_f32_e32 v137, 0x3f317217, v136
	v_mov_b32_e32 v136, v137
	v_mul_f32_e32 v137, 0xbfb8aa3b, v57
	v_exp_f32_e32 v137, v137
	s_nop 0
	v_add_f32_e32 v137, 1.0, v137
	v_rcp_f32_e32 v137, v137
	s_nop 0
	v_fma_f32 v137, v137, v198, v197
	v_log_f32_e32 v137, v137
	s_nop 0
	v_mul_f32_e32 v199, 0x3f317217, v137
	v_fma_f32 v199, v137, s62, -v199
	v_fmac_f32_e32 v199, 0x3377d1cf, v137
	v_fmac_f32_e32 v199, 0x3f317217, v137
	v_mov_b32_e32 v137, v199
	global_store_dwordx4 v[162:163], v[134:137], off offset:512
	s_nop 1
	v_mul_f32_e32 v134, 0xbfb8aa3b, v38
	v_exp_f32_e32 v134, v134
	s_nop 0
	v_add_f32_e32 v134, 1.0, v134
	v_rcp_f32_e32 v134, v134
	s_nop 0
	v_fma_f32 v134, v134, v151, v0
	v_log_f32_e32 v134, v134
	s_nop 0
	v_mul_f32_e32 v135, 0x3f317217, v134
	v_fma_f32 v135, v134, s62, -v135
	v_fmac_f32_e32 v135, 0x3377d1cf, v134
	v_fmac_f32_e32 v135, 0x3f317217, v134
	v_mov_b32_e32 v134, v135
	v_mul_f32_e32 v135, 0xbfb8aa3b, v39
	v_exp_f32_e32 v135, v135
	s_nop 0
	v_add_f32_e32 v135, 1.0, v135
	v_rcp_f32_e32 v135, v135
	s_nop 0
	v_fma_f32 v135, v135, v194, v153
	v_log_f32_e32 v135, v135
	s_nop 0
	v_mul_f32_e32 v136, 0x3f317217, v135
	v_fma_f32 v136, v135, s62, -v136
	v_fmac_f32_e32 v136, 0x3377d1cf, v135
	v_fmac_f32_e32 v136, 0x3f317217, v135
	v_mov_b32_e32 v135, v136
	v_mul_f32_e32 v136, 0xbfb8aa3b, v40
	v_exp_f32_e32 v136, v136
	s_nop 0
	v_add_f32_e32 v136, 1.0, v136
	v_rcp_f32_e32 v136, v136
	s_nop 0
	v_fma_f32 v136, v136, v196, v195
	v_log_f32_e32 v136, v136
	s_nop 0
	v_mul_f32_e32 v137, 0x3f317217, v136
	v_fma_f32 v137, v136, s62, -v137
	v_fmac_f32_e32 v137, 0x3377d1cf, v136
	v_fmac_f32_e32 v137, 0x3f317217, v136
	v_mov_b32_e32 v136, v137
	v_mul_f32_e32 v137, 0xbfb8aa3b, v41
	v_exp_f32_e32 v137, v137
	s_nop 0
	v_add_f32_e32 v137, 1.0, v137
	v_rcp_f32_e32 v137, v137
	s_nop 0
	v_fma_f32 v137, v137, v198, v197
	v_log_f32_e32 v137, v137
	s_nop 0
	v_mul_f32_e32 v199, 0x3f317217, v137
	v_fma_f32 v199, v137, s62, -v199
	v_fmac_f32_e32 v199, 0x3377d1cf, v137
	v_fmac_f32_e32 v199, 0x3f317217, v137
	v_mov_b32_e32 v137, v199
	global_store_dwordx4 v[164:165], v[134:137], off offset:512
	s_nop 1
	v_mul_f32_e32 v134, 0xbfb8aa3b, v22
	v_exp_f32_e32 v134, v134
	s_nop 0
	v_add_f32_e32 v134, 1.0, v134
	v_rcp_f32_e32 v134, v134
	s_nop 0
	v_fma_f32 v134, v134, v151, v0
	v_log_f32_e32 v134, v134
	s_nop 0
	v_mul_f32_e32 v135, 0x3f317217, v134
	v_fma_f32 v135, v134, s62, -v135
	v_fmac_f32_e32 v135, 0x3377d1cf, v134
	v_fmac_f32_e32 v135, 0x3f317217, v134
	v_mov_b32_e32 v134, v135
	v_mul_f32_e32 v135, 0xbfb8aa3b, v23
	v_exp_f32_e32 v135, v135
	s_nop 0
	v_add_f32_e32 v135, 1.0, v135
	v_rcp_f32_e32 v135, v135
	s_nop 0
	v_fma_f32 v135, v135, v194, v153
	v_log_f32_e32 v135, v135
	s_nop 0
	v_mul_f32_e32 v136, 0x3f317217, v135
	v_fma_f32 v136, v135, s62, -v136
	v_fmac_f32_e32 v136, 0x3377d1cf, v135
	v_fmac_f32_e32 v136, 0x3f317217, v135
	v_mov_b32_e32 v135, v136
	v_mul_f32_e32 v136, 0xbfb8aa3b, v24
	v_exp_f32_e32 v136, v136
	s_nop 0
	v_add_f32_e32 v136, 1.0, v136
	v_rcp_f32_e32 v136, v136
	s_nop 0
	v_fma_f32 v136, v136, v196, v195
	v_log_f32_e32 v136, v136
	s_nop 0
	v_mul_f32_e32 v137, 0x3f317217, v136
	v_fma_f32 v137, v136, s62, -v137
	v_fmac_f32_e32 v137, 0x3377d1cf, v136
	v_fmac_f32_e32 v137, 0x3f317217, v136
	v_mov_b32_e32 v136, v137
	v_mul_f32_e32 v137, 0xbfb8aa3b, v25
	v_exp_f32_e32 v137, v137
	s_nop 0
	v_add_f32_e32 v137, 1.0, v137
	v_rcp_f32_e32 v137, v137
	s_nop 0
	v_fma_f32 v137, v137, v198, v197
; __device__ __forceinline__ float sigm(float x) { return __builtin_amdgcn_rcpf(1.f + fexp(-x)); }
;   __device__ __forceinline__ void operator()(const AccT& acc, int pm, int pn, int wr, int wc, int fr, int fq) const {
;     ...
;       const int dir = seg - 1;
;       float* GF = (float*)(ws + OFF_GF);
;       const float* LB = (const float*)(ws + OFF_LB) + l * 1024 + dir * 512;
; #pragma unroll
;       for (int bj = 0; bj < 2; ++bj)
; #pragma unroll
;         for (int n = 0; n < 2; ++n) { const int c = cin + bj * 128 + n * 4; const f32x4 lb = *(const f32x4*)(LB + c);
; #pragma unroll
;           for (int ai = 0; ai < 2; ++ai)
; #pragma unroll
;             for (int m = 0; m < 4; ++m) { const f32x4 v = acc[ai][bj][m][n]; f32x4 o;
; #pragma unroll
;               for (int j = 0; j < 4; ++j) o[j] = __logf(fmaxf(lb[j], 1e-30f) + (1.f - lb[j]) * sigm(v[j]));
;               *(f32x4*)(GF + (size_t)(row0 + ai * 128 + m * 16) * 1024 + dir * 512 + c) = o; } }
	v_log_f32_e32 v137, v137
	s_nop 0
	v_mul_f32_e32 v199, 0x3f317217, v137
	v_fma_f32 v199, v137, s62, -v199
	v_fmac_f32_e32 v199, 0x3377d1cf, v137
	v_fmac_f32_e32 v199, 0x3f317217, v137
	v_mov_b32_e32 v137, v199
	global_store_dwordx4 v[168:169], v[134:137], off offset:512
	s_nop 1
	v_mul_f32_e32 v134, 0xbfb8aa3b, v6
	v_exp_f32_e32 v134, v134
	s_nop 0
	v_add_f32_e32 v134, 1.0, v134
	v_rcp_f32_e32 v134, v134
	s_nop 0
	v_fmac_f32_e32 v0, v134, v151
	v_cmp_gt_f32_e32 vcc, s63, v0
	v_sub_f32_e32 v151, 1.0, v132
	s_nop 0
	v_cndmask_b32_e64 v134, 0, 32, vcc
	v_ldexp_f32 v0, v0, v134
	v_log_f32_e32 v0, v0
	s_nop 0
	v_mul_f32_e32 v134, 0x3f317217, v0
	v_fma_f32 v134, v0, s62, -v134
	v_fmac_f32_e32 v134, 0x3377d1cf, v0
	v_fmac_f32_e32 v134, 0x3f317217, v0
	v_cmp_lt_f32_e64 s[0:1], |v0|, s94
	s_nop 1
	v_cndmask_b32_e64 v0, v0, v134, s[0:1]
	v_cndmask_b32_e32 v134, 0, v186, vcc
	v_sub_f32_e32 v134, v0, v134
	v_mul_f32_e32 v0, 0xbfb8aa3b, v7
	v_exp_f32_e32 v0, v0
	s_nop 0
	v_add_f32_e32 v0, 1.0, v0
	v_rcp_f32_e32 v0, v0
	s_nop 0
	v_fmac_f32_e32 v153, v0, v194
	v_cmp_gt_f32_e32 vcc, s63, v153
	v_sub_f32_e32 v194, 1.0, v133
	s_nop 0
	v_cndmask_b32_e64 v0, 0, 32, vcc
	v_ldexp_f32 v0, v153, v0
	v_log_f32_e32 v0, v0
	s_nop 0
	v_mul_f32_e32 v135, 0x3f317217, v0
	v_fma_f32 v135, v0, s62, -v135
	v_fmac_f32_e32 v135, 0x3377d1cf, v0
	v_fmac_f32_e32 v135, 0x3f317217, v0
	v_cmp_lt_f32_e64 s[0:1], |v0|, s94
	s_nop 1
	v_cndmask_b32_e64 v0, v0, v135, s[0:1]
	v_cndmask_b32_e32 v135, 0, v186, vcc
	v_sub_f32_e32 v135, v0, v135
	v_mul_f32_e32 v0, 0xbfb8aa3b, v8
	v_exp_f32_e32 v0, v0
	s_nop 0
	v_add_f32_e32 v0, 1.0, v0
	v_rcp_f32_e32 v0, v0
	s_nop 0
	v_fmac_f32_e32 v195, v0, v196
	v_log_f32_e32 v0, v195
	s_nop 0
	v_mul_f32_e32 v136, 0x3f317217, v0
	v_fma_f32 v136, v0, s62, -v136
	v_fmac_f32_e32 v136, 0x3377d1cf, v0
	v_fmac_f32_e32 v136, 0x3f317217, v0
	v_mul_f32_e32 v0, 0xbfb8aa3b, v9
	v_exp_f32_e32 v0, v0
	s_nop 0
	v_add_f32_e32 v0, 1.0, v0
	v_rcp_f32_e32 v0, v0
	s_nop 0
	v_fmac_f32_e32 v197, v0, v198
	v_log_f32_e32 v0, v197
	s_nop 0
	v_mul_f32_e32 v137, 0x3f317217, v0
	v_fma_f32 v137, v0, s62, -v137
	v_fmac_f32_e32 v137, 0x3377d1cf, v0
	v_fmac_f32_e32 v137, 0x3f317217, v0
	global_store_dwordx4 v[166:167], v[134:137], off offset:512
	v_max_f32_e32 v0, v130, v130
	v_max_f32_e32 v0, 0xda24260, v0
	v_sub_f32_e32 v134, 1.0, v130
	v_mul_f32_e32 v130, 0xbfb8aa3b, v114
	v_exp_f32_e32 v130, v130
	v_sub_f32_e32 v136, 1.0, v131
	v_add_f32_e32 v130, 1.0, v130
	v_rcp_f32_e32 v130, v130
	s_nop 0
	v_fma_f32 v130, v130, v134, v0
	v_log_f32_e32 v130, v130
	s_nop 0
	v_mul_f32_e32 v135, 0x3f317217, v130
	v_fma_f32 v135, v130, s62, -v135
	v_fmac_f32_e32 v135, 0x3377d1cf, v130
	v_fmac_f32_e32 v135, 0x3f317217, v130
	v_mov_b32_e32 v130, v135
	v_max_f32_e32 v135, v131, v131
	v_mul_f32_e32 v131, 0xbfb8aa3b, v115
	v_exp_f32_e32 v131, v131
	v_max_f32_e32 v135, 0xda24260, v135
	v_add_f32_e32 v131, 1.0, v131
	v_rcp_f32_e32 v131, v131
	s_nop 0
	v_fma_f32 v131, v131, v136, v135
	v_log_f32_e32 v131, v131
	s_nop 0
	v_mul_f32_e32 v137, 0x3f317217, v131
	v_fma_f32 v137, v131, s62, -v137
	v_fmac_f32_e32 v137, 0x3377d1cf, v131
	v_fmac_f32_e32 v137, 0x3f317217, v131
	v_mov_b32_e32 v131, v137
	v_max_f32_e32 v137, v132, v132
	v_mul_f32_e32 v132, 0xbfb8aa3b, v116
	v_exp_f32_e32 v132, v132
	v_max_f32_e32 v137, 0xda24260, v137
	v_add_f32_e32 v132, 1.0, v132
	v_rcp_f32_e32 v132, v132
	s_nop 0
	v_fma_f32 v132, v132, v151, v137
	v_log_f32_e32 v132, v132
	s_nop 0
	v_mul_f32_e32 v153, 0x3f317217, v132
	v_fma_f32 v153, v132, s62, -v153
	v_fmac_f32_e32 v153, 0x3377d1cf, v132
	v_fmac_f32_e32 v153, 0x3f317217, v132
	v_mov_b32_e32 v132, v153
	v_max_f32_e32 v153, v133, v133
	v_mul_f32_e32 v133, 0xbfb8aa3b, v117
	v_exp_f32_e32 v133, v133
	v_max_f32_e32 v153, 0xda24260, v153
	v_add_f32_e32 v133, 1.0, v133
	v_rcp_f32_e32 v133, v133
	s_nop 0
	v_fma_f32 v133, v133, v194, v153
	v_log_f32_e32 v133, v133
	s_nop 0
	v_mul_f32_e32 v195, 0x3f317217, v133
	v_fma_f32 v195, v133, s62, -v195
	v_fmac_f32_e32 v195, 0x3377d1cf, v133
	v_fmac_f32_e32 v195, 0x3f317217, v133
	v_mov_b32_e32 v133, v195
	global_store_dwordx4 v[154:155], v[130:133], off offset:528
	s_nop 1
	v_mul_f32_e32 v130, 0xbfb8aa3b, v98
	v_exp_f32_e32 v130, v130
	s_nop 0
	v_add_f32_e32 v130, 1.0, v130
	v_rcp_f32_e32 v130, v130
	s_nop 0
	v_fma_f32 v130, v130, v134, v0
	v_log_f32_e32 v130, v130
	s_nop 0
	v_mul_f32_e32 v131, 0x3f317217, v130
	v_fma_f32 v131, v130, s62, -v131
	v_fmac_f32_e32 v131, 0x3377d1cf, v130
	v_fmac_f32_e32 v131, 0x3f317217, v130
	v_mov_b32_e32 v130, v131
	v_mul_f32_e32 v131, 0xbfb8aa3b, v99
	v_exp_f32_e32 v131, v131
	s_nop 0
	v_add_f32_e32 v131, 1.0, v131
	v_rcp_f32_e32 v131, v131
	s_nop 0
	v_fma_f32 v131, v131, v136, v135
	v_log_f32_e32 v131, v131
	s_nop 0
	v_mul_f32_e32 v132, 0x3f317217, v131
	v_fma_f32 v132, v131, s62, -v132
	v_fmac_f32_e32 v132, 0x3377d1cf, v131
	v_fmac_f32_e32 v132, 0x3f317217, v131
	v_mov_b32_e32 v131, v132
	v_mul_f32_e32 v132, 0xbfb8aa3b, v100
	v_exp_f32_e32 v132, v132
	s_nop 0
	v_add_f32_e32 v132, 1.0, v132
	v_rcp_f32_e32 v132, v132
	s_nop 0
	v_fma_f32 v132, v132, v151, v137
	v_log_f32_e32 v132, v132
	s_nop 0
	v_mul_f32_e32 v133, 0x3f317217, v132
	v_fma_f32 v133, v132, s62, -v133
	v_fmac_f32_e32 v133, 0x3377d1cf, v132
	v_fmac_f32_e32 v133, 0x3f317217, v132
	v_mov_b32_e32 v132, v133
	v_mul_f32_e32 v133, 0xbfb8aa3b, v101
	v_exp_f32_e32 v133, v133
	s_nop 0
	v_add_f32_e32 v133, 1.0, v133
	v_rcp_f32_e32 v133, v133
	s_nop 0
	v_fma_f32 v133, v133, v194, v153
	v_log_f32_e32 v133, v133
	s_nop 0
	v_mul_f32_e32 v154, 0x3f317217, v133
	v_fma_f32 v154, v133, s62, -v154
	v_fmac_f32_e32 v154, 0x3377d1cf, v133
	v_fmac_f32_e32 v154, 0x3f317217, v133
; __device__ __forceinline__ float sigm(float x) { return __builtin_amdgcn_rcpf(1.f + fexp(-x)); }
;   __device__ __forceinline__ void operator()(const AccT& acc, int pm, int pn, int wr, int wc, int fr, int fq) const {
;     ...
;       const int dir = seg - 1;
;       float* GF = (float*)(ws + OFF_GF);
;       const float* LB = (const float*)(ws + OFF_LB) + l * 1024 + dir * 512;
; #pragma unroll
;       for (int bj = 0; bj < 2; ++bj)
; #pragma unroll
;         for (int n = 0; n < 2; ++n) { const int c = cin + bj * 128 + n * 4; const f32x4 lb = *(const f32x4*)(LB + c);
; #pragma unroll
;           for (int ai = 0; ai < 2; ++ai)
; #pragma unroll
;             for (int m = 0; m < 4; ++m) { const f32x4 v = acc[ai][bj][m][n]; f32x4 o;
; #pragma unroll
;               for (int j = 0; j < 4; ++j) o[j] = __logf(fmaxf(lb[j], 1e-30f) + (1.f - lb[j]) * sigm(v[j]));
;               *(f32x4*)(GF + (size_t)(row0 + ai * 128 + m * 16) * 1024 + dir * 512 + c) = o; } }
	v_mov_b32_e32 v133, v154
	global_store_dwordx4 v[156:157], v[130:133], off offset:528
	s_nop 1
	v_mul_f32_e32 v130, 0xbfb8aa3b, v82
	v_exp_f32_e32 v130, v130
	s_nop 0
	v_add_f32_e32 v130, 1.0, v130
	v_rcp_f32_e32 v130, v130
	s_nop 0
	v_fma_f32 v130, v130, v134, v0
	v_log_f32_e32 v130, v130
	s_nop 0
	v_mul_f32_e32 v131, 0x3f317217, v130
	v_fma_f32 v131, v130, s62, -v131
	v_fmac_f32_e32 v131, 0x3377d1cf, v130
	v_fmac_f32_e32 v131, 0x3f317217, v130
	v_mov_b32_e32 v130, v131
	v_mul_f32_e32 v131, 0xbfb8aa3b, v83
	v_exp_f32_e32 v131, v131
	s_nop 0
	v_add_f32_e32 v131, 1.0, v131
	v_rcp_f32_e32 v131, v131
	s_nop 0
	v_fma_f32 v131, v131, v136, v135
	v_log_f32_e32 v131, v131
	s_nop 0
	v_mul_f32_e32 v132, 0x3f317217, v131
	v_fma_f32 v132, v131, s62, -v132
	v_fmac_f32_e32 v132, 0x3377d1cf, v131
	v_fmac_f32_e32 v132, 0x3f317217, v131
	v_mov_b32_e32 v131, v132
	v_mul_f32_e32 v132, 0xbfb8aa3b, v84
	v_exp_f32_e32 v132, v132
	s_nop 0
	v_add_f32_e32 v132, 1.0, v132
	v_rcp_f32_e32 v132, v132
	s_nop 0
	v_fma_f32 v132, v132, v151, v137
	v_log_f32_e32 v132, v132
	s_nop 0
	v_mul_f32_e32 v133, 0x3f317217, v132
	v_fma_f32 v133, v132, s62, -v133
	v_fmac_f32_e32 v133, 0x3377d1cf, v132
	v_fmac_f32_e32 v133, 0x3f317217, v132
	v_mov_b32_e32 v132, v133
	v_mul_f32_e32 v133, 0xbfb8aa3b, v85
	v_exp_f32_e32 v133, v133
	s_nop 0
	v_add_f32_e32 v133, 1.0, v133
	v_rcp_f32_e32 v133, v133
	s_nop 0
	v_fma_f32 v133, v133, v194, v153
	v_log_f32_e32 v133, v133
	s_nop 0
	v_mul_f32_e32 v154, 0x3f317217, v133
	v_fma_f32 v154, v133, s62, -v154
	v_fmac_f32_e32 v154, 0x3377d1cf, v133
	v_fmac_f32_e32 v154, 0x3f317217, v133
	v_mov_b32_e32 v133, v154
	global_store_dwordx4 v[158:159], v[130:133], off offset:528
	s_nop 1
	v_mul_f32_e32 v130, 0xbfb8aa3b, v66
	v_exp_f32_e32 v130, v130
	s_nop 0
	v_add_f32_e32 v130, 1.0, v130
	v_rcp_f32_e32 v130, v130
	s_nop 0
	v_fma_f32 v130, v130, v134, v0
	v_log_f32_e32 v130, v130
	s_nop 0
	v_mul_f32_e32 v131, 0x3f317217, v130
	v_fma_f32 v131, v130, s62, -v131
	v_fmac_f32_e32 v131, 0x3377d1cf, v130
	v_fmac_f32_e32 v131, 0x3f317217, v130
	v_mov_b32_e32 v130, v131
	v_mul_f32_e32 v131, 0xbfb8aa3b, v67
	v_exp_f32_e32 v131, v131
	s_nop 0
	v_add_f32_e32 v131, 1.0, v131
	v_rcp_f32_e32 v131, v131
	s_nop 0
	v_fma_f32 v131, v131, v136, v135
	v_log_f32_e32 v131, v131
	s_nop 0
	v_mul_f32_e32 v132, 0x3f317217, v131
	v_fma_f32 v132, v131, s62, -v132
	v_fmac_f32_e32 v132, 0x3377d1cf, v131
	v_fmac_f32_e32 v132, 0x3f317217, v131
	v_mov_b32_e32 v131, v132
	v_mul_f32_e32 v132, 0xbfb8aa3b, v68
	v_exp_f32_e32 v132, v132
	s_nop 0
	v_add_f32_e32 v132, 1.0, v132
	v_rcp_f32_e32 v132, v132
	s_nop 0
	v_fma_f32 v132, v132, v151, v137
	v_log_f32_e32 v132, v132
	s_nop 0
	v_mul_f32_e32 v133, 0x3f317217, v132
	v_fma_f32 v133, v132, s62, -v133
	v_fmac_f32_e32 v133, 0x3377d1cf, v132
	v_fmac_f32_e32 v133, 0x3f317217, v132
	v_mov_b32_e32 v132, v133
	v_mul_f32_e32 v133, 0xbfb8aa3b, v69
	v_exp_f32_e32 v133, v133
	s_nop 0
	v_add_f32_e32 v133, 1.0, v133
	v_rcp_f32_e32 v133, v133
	s_nop 0
	v_fma_f32 v133, v133, v194, v153
	v_log_f32_e32 v133, v133
	s_nop 0
	v_mul_f32_e32 v154, 0x3f317217, v133
	v_fma_f32 v154, v133, s62, -v154
	v_fmac_f32_e32 v154, 0x3377d1cf, v133
	v_fmac_f32_e32 v154, 0x3f317217, v133
	v_mov_b32_e32 v133, v154
	global_store_dwordx4 v[160:161], v[130:133], off offset:528
	s_nop 1
	v_mul_f32_e32 v130, 0xbfb8aa3b, v50
	v_exp_f32_e32 v130, v130
	s_nop 0
	v_add_f32_e32 v130, 1.0, v130
	v_rcp_f32_e32 v130, v130
	s_nop 0
	v_fma_f32 v130, v130, v134, v0
	v_log_f32_e32 v130, v130
	s_nop 0
	v_mul_f32_e32 v131, 0x3f317217, v130
	v_fma_f32 v131, v130, s62, -v131
	v_fmac_f32_e32 v131, 0x3377d1cf, v130
	v_fmac_f32_e32 v131, 0x3f317217, v130
	v_mov_b32_e32 v130, v131
	v_mul_f32_e32 v131, 0xbfb8aa3b, v51
	v_exp_f32_e32 v131, v131
	s_nop 0
	v_add_f32_e32 v131, 1.0, v131
	v_rcp_f32_e32 v131, v131
	s_nop 0
	v_fma_f32 v131, v131, v136, v135
	v_log_f32_e32 v131, v131
	s_nop 0
	v_mul_f32_e32 v132, 0x3f317217, v131
	v_fma_f32 v132, v131, s62, -v132
	v_fmac_f32_e32 v132, 0x3377d1cf, v131
	v_fmac_f32_e32 v132, 0x3f317217, v131
	v_mov_b32_e32 v131, v132
	v_mul_f32_e32 v132, 0xbfb8aa3b, v52
	v_exp_f32_e32 v132, v132
	s_nop 0
	v_add_f32_e32 v132, 1.0, v132
	v_rcp_f32_e32 v132, v132
	s_nop 0
	v_fma_f32 v132, v132, v151, v137
	v_log_f32_e32 v132, v132
	s_nop 0
	v_mul_f32_e32 v133, 0x3f317217, v132
	v_fma_f32 v133, v132, s62, -v133
	v_fmac_f32_e32 v133, 0x3377d1cf, v132
	v_fmac_f32_e32 v133, 0x3f317217, v132
	v_mov_b32_e32 v132, v133
	v_mul_f32_e32 v133, 0xbfb8aa3b, v53
	v_exp_f32_e32 v133, v133
	s_nop 0
	v_add_f32_e32 v133, 1.0, v133
	v_rcp_f32_e32 v133, v133
	s_nop 0
	v_fma_f32 v133, v133, v194, v153
	v_log_f32_e32 v133, v133
	s_nop 0
	v_mul_f32_e32 v154, 0x3f317217, v133
	v_fma_f32 v154, v133, s62, -v154
	v_fmac_f32_e32 v154, 0x3377d1cf, v133
; __device__ __forceinline__ float sigm(float x) { return __builtin_amdgcn_rcpf(1.f + fexp(-x)); }
;   __device__ __forceinline__ void operator()(const AccT& acc, int pm, int pn, int wr, int wc, int fr, int fq) const {
;     ...
;       const int dir = seg - 1;
;       float* GF = (float*)(ws + OFF_GF);
;       const float* LB = (const float*)(ws + OFF_LB) + l * 1024 + dir * 512;
; #pragma unroll
;       for (int bj = 0; bj < 2; ++bj)
; #pragma unroll
;         for (int n = 0; n < 2; ++n) { const int c = cin + bj * 128 + n * 4; const f32x4 lb = *(const f32x4*)(LB + c);
; #pragma unroll
;           for (int ai = 0; ai < 2; ++ai)
; #pragma unroll
;             for (int m = 0; m < 4; ++m) { const f32x4 v = acc[ai][bj][m][n]; f32x4 o;
; #pragma unroll
;               for (int j = 0; j < 4; ++j) o[j] = __logf(fmaxf(lb[j], 1e-30f) + (1.f - lb[j]) * sigm(v[j]));
;               *(f32x4*)(GF + (size_t)(row0 + ai * 128 + m * 16) * 1024 + dir * 512 + c) = o; } }
	v_fmac_f32_e32 v154, 0x3f317217, v133
	v_mov_b32_e32 v133, v154
	global_store_dwordx4 v[162:163], v[130:133], off offset:528
	s_nop 1
	v_mul_f32_e32 v130, 0xbfb8aa3b, v34
	v_exp_f32_e32 v130, v130
	s_nop 0
	v_add_f32_e32 v130, 1.0, v130
	v_rcp_f32_e32 v130, v130
	s_nop 0
	v_fma_f32 v130, v130, v134, v0
	v_log_f32_e32 v130, v130
	s_nop 0
	v_mul_f32_e32 v131, 0x3f317217, v130
	v_fma_f32 v131, v130, s62, -v131
	v_fmac_f32_e32 v131, 0x3377d1cf, v130
	v_fmac_f32_e32 v131, 0x3f317217, v130
	v_mov_b32_e32 v130, v131
	v_mul_f32_e32 v131, 0xbfb8aa3b, v35
	v_exp_f32_e32 v131, v131
	s_nop 0
	v_add_f32_e32 v131, 1.0, v131
	v_rcp_f32_e32 v131, v131
	s_nop 0
	v_fma_f32 v131, v131, v136, v135
	v_log_f32_e32 v131, v131
	s_nop 0
	v_mul_f32_e32 v132, 0x3f317217, v131
	v_fma_f32 v132, v131, s62, -v132
	v_fmac_f32_e32 v132, 0x3377d1cf, v131
	v_fmac_f32_e32 v132, 0x3f317217, v131
	v_mov_b32_e32 v131, v132
	v_mul_f32_e32 v132, 0xbfb8aa3b, v36
	v_exp_f32_e32 v132, v132
	s_nop 0
	v_add_f32_e32 v132, 1.0, v132
	v_rcp_f32_e32 v132, v132
	s_nop 0
	v_fma_f32 v132, v132, v151, v137
	v_log_f32_e32 v132, v132
	s_nop 0
	v_mul_f32_e32 v133, 0x3f317217, v132
	v_fma_f32 v133, v132, s62, -v133
	v_fmac_f32_e32 v133, 0x3377d1cf, v132
	v_fmac_f32_e32 v133, 0x3f317217, v132
	v_mov_b32_e32 v132, v133
	v_mul_f32_e32 v133, 0xbfb8aa3b, v37
	v_exp_f32_e32 v133, v133
	s_nop 0
	v_add_f32_e32 v133, 1.0, v133
	v_rcp_f32_e32 v133, v133
	s_nop 0
	v_fma_f32 v133, v133, v194, v153
	v_log_f32_e32 v133, v133
	s_nop 0
	v_mul_f32_e32 v154, 0x3f317217, v133
	v_fma_f32 v154, v133, s62, -v154
	v_fmac_f32_e32 v154, 0x3377d1cf, v133
	v_fmac_f32_e32 v154, 0x3f317217, v133
	v_mov_b32_e32 v133, v154
	global_store_dwordx4 v[164:165], v[130:133], off offset:528
	s_nop 1
	v_mul_f32_e32 v130, 0xbfb8aa3b, v18
	v_exp_f32_e32 v130, v130
	s_nop 0
	v_add_f32_e32 v130, 1.0, v130
	v_rcp_f32_e32 v130, v130
	s_nop 0
	v_fma_f32 v130, v130, v134, v0
	v_log_f32_e32 v130, v130
	s_nop 0
	v_mul_f32_e32 v131, 0x3f317217, v130
	v_fma_f32 v131, v130, s62, -v131
	v_fmac_f32_e32 v131, 0x3377d1cf, v130
	v_fmac_f32_e32 v131, 0x3f317217, v130
	v_mov_b32_e32 v130, v131
	v_mul_f32_e32 v131, 0xbfb8aa3b, v19
	v_exp_f32_e32 v131, v131
	s_nop 0
	v_add_f32_e32 v131, 1.0, v131
	v_rcp_f32_e32 v131, v131
	s_nop 0
	v_fma_f32 v131, v131, v136, v135
	v_log_f32_e32 v131, v131
	s_nop 0
	v_mul_f32_e32 v132, 0x3f317217, v131
	v_fma_f32 v132, v131, s62, -v132
	v_fmac_f32_e32 v132, 0x3377d1cf, v131
	v_fmac_f32_e32 v132, 0x3f317217, v131
	v_mov_b32_e32 v131, v132
	v_mul_f32_e32 v132, 0xbfb8aa3b, v20
	v_exp_f32_e32 v132, v132
	s_nop 0
	v_add_f32_e32 v132, 1.0, v132
	v_rcp_f32_e32 v132, v132
	s_nop 0
	v_fma_f32 v132, v132, v151, v137
	v_log_f32_e32 v132, v132
	s_nop 0
	v_mul_f32_e32 v133, 0x3f317217, v132
	v_fma_f32 v133, v132, s62, -v133
	v_fmac_f32_e32 v133, 0x3377d1cf, v132
	v_fmac_f32_e32 v133, 0x3f317217, v132
	v_mov_b32_e32 v132, v133
	v_mul_f32_e32 v133, 0xbfb8aa3b, v21
	v_exp_f32_e32 v133, v133
	s_nop 0
	v_add_f32_e32 v133, 1.0, v133
	v_rcp_f32_e32 v133, v133
	s_nop 0
	v_fma_f32 v133, v133, v194, v153
	v_log_f32_e32 v133, v133
	s_nop 0
	v_mul_f32_e32 v154, 0x3f317217, v133
	v_fma_f32 v154, v133, s62, -v154
	v_fmac_f32_e32 v154, 0x3377d1cf, v133
	v_fmac_f32_e32 v154, 0x3f317217, v133
	v_mov_b32_e32 v133, v154
	global_store_dwordx4 v[168:169], v[130:133], off offset:528
	s_nop 1
	v_mul_f32_e32 v130, 0xbfb8aa3b, v2
	v_exp_f32_e32 v130, v130
	s_nop 0
	v_add_f32_e32 v130, 1.0, v130
	v_rcp_f32_e32 v130, v130
	s_nop 0
	v_fmac_f32_e32 v0, v130, v134
	v_log_f32_e32 v0, v0
	s_nop 0
	v_mul_f32_e32 v130, 0x3f317217, v0
	v_fma_f32 v130, v0, s62, -v130
	v_fmac_f32_e32 v130, 0x3377d1cf, v0
	v_fmac_f32_e32 v130, 0x3f317217, v0
	v_mul_f32_e32 v0, 0xbfb8aa3b, v3
	v_exp_f32_e32 v0, v0
	s_nop 0
	v_add_f32_e32 v0, 1.0, v0
	v_rcp_f32_e32 v0, v0
	s_nop 0
	v_fmac_f32_e32 v135, v0, v136
	v_log_f32_e32 v0, v135
	s_nop 0
	v_mul_f32_e32 v131, 0x3f317217, v0
	v_fma_f32 v131, v0, s62, -v131
	v_fmac_f32_e32 v131, 0x3377d1cf, v0
	v_fmac_f32_e32 v131, 0x3f317217, v0
	v_mul_f32_e32 v0, 0xbfb8aa3b, v4
	v_exp_f32_e32 v0, v0
	s_nop 0
	v_add_f32_e32 v0, 1.0, v0
	v_rcp_f32_e32 v0, v0
	s_nop 0
	v_fmac_f32_e32 v137, v0, v151
	v_log_f32_e32 v0, v137
	s_nop 0
	v_mul_f32_e32 v132, 0x3f317217, v0
	v_fma_f32 v132, v0, s62, -v132
	v_fmac_f32_e32 v132, 0x3377d1cf, v0
	v_fmac_f32_e32 v132, 0x3f317217, v0
	v_mul_f32_e32 v0, 0xbfb8aa3b, v5
	v_exp_f32_e32 v0, v0
	s_nop 0
	v_add_f32_e32 v0, 1.0, v0
	v_rcp_f32_e32 v0, v0
	s_nop 0
	v_fmac_f32_e32 v153, v0, v194
	v_log_f32_e32 v0, v153
	s_nop 0
	v_mul_f32_e32 v133, 0x3f317217, v0
	v_fma_f32 v133, v0, s62, -v133
	v_fmac_f32_e32 v133, 0x3377d1cf, v0
	v_fmac_f32_e32 v133, 0x3f317217, v0
	global_store_dwordx4 v[166:167], v[130:133], off offset:528
